# all fp32->bf16 transpose/convert loops (prep phases and idle-WG weight conversion): dwordx4 stores write-through (sc1)
# baseline (speedup 1.0000x reference)
.LBB0_116:
	s_or_b64 exec, exec, s[36:37]
	s_waitcnt vmcnt(0)
	ds_write2_b32 v19, v2, v3 offset1:1
	ds_write2_b32 v19, v4, v5 offset0:2 offset1:3
	ds_write2_b32 v20, v6, v7 offset1:1
	ds_write2_b32 v20, v8, v9 offset0:2 offset1:3
	ds_write2_b32 v21, v10, v11 offset1:1
	ds_write2_b32 v21, v12, v13 offset0:2 offset1:3
	ds_write2_b32 v22, v14, v15 offset1:1
	ds_write2_b32 v22, v16, v17 offset0:2 offset1:3
	s_waitcnt lgkmcnt(0)
	s_barrier
	ds_read2_b32 v[2:3], v18 offset1:65
	ds_read2_b32 v[4:5], v18 offset0:130 offset1:195
	v_add_u32_e32 v8, 0x400, v18
	ds_read2_b32 v[6:7], v8 offset0:4 offset1:69
	ds_read2_b32 v[8:9], v8 offset0:134 offset1:199
	s_mul_hi_i32 s35, s27, 0x6c0000
	s_waitcnt lgkmcnt(3)
	v_and_b32_sdwa v26, v2, v193 dst_sel:DWORD dst_unused:UNUSED_PAD src0_sel:WORD_1 src1_sel:DWORD
	s_waitcnt lgkmcnt(2)
	v_and_b32_sdwa v23, v4, v193 dst_sel:DWORD dst_unused:UNUSED_PAD src0_sel:WORD_1 src1_sel:DWORD
	v_add3_u32 v4, v4, v23, s87
	v_and_b32_sdwa v23, v5, v193 dst_sel:DWORD dst_unused:UNUSED_PAD src0_sel:WORD_1 src1_sel:DWORD
	v_add3_u32 v2, v2, v26, s87
	v_and_b32_sdwa v26, v3, v193 dst_sel:DWORD dst_unused:UNUSED_PAD src0_sel:WORD_1 src1_sel:DWORD
	v_add3_u32 v5, v5, v23, s87
	s_mul_i32 s27, s27, 0x6c0000
	v_or_b32_e32 v24, s34, v147
	v_add3_u32 v3, v3, v26, s87
	v_and_b32_e32 v5, 0xffff0000, v5
	s_add_u32 s36, s14, s27
	v_add_u32_e32 v12, 0x800, v18
	v_ashrrev_i32_e32 v25, 31, v24
	v_and_b32_e32 v23, 0xffff0000, v3
	v_or_b32_sdwa v3, v5, v4 dst_sel:DWORD dst_unused:UNUSED_PAD src0_sel:DWORD src1_sel:WORD_1
	s_waitcnt lgkmcnt(0)
	v_and_b32_sdwa v4, v8, v193 dst_sel:DWORD dst_unused:UNUSED_PAD src0_sel:WORD_1 src1_sel:DWORD
	v_and_b32_sdwa v5, v6, v193 dst_sel:DWORD dst_unused:UNUSED_PAD src0_sel:WORD_1 src1_sel:DWORD
	s_addc_u32 s37, s19, s35
	ds_read2_b32 v[10:11], v12 offset0:8 offset1:73
	ds_read2_b32 v[12:13], v12 offset0:138 offset1:203
	v_lshlrev_b64 v[24:25], 11, v[24:25]
	v_add3_u32 v6, v6, v5, s87
	v_add3_u32 v4, v8, v4, s87
	v_and_b32_sdwa v5, v9, v193 dst_sel:DWORD dst_unused:UNUSED_PAD src0_sel:WORD_1 src1_sel:DWORD
	v_and_b32_sdwa v8, v7, v193 dst_sel:DWORD dst_unused:UNUSED_PAD src0_sel:WORD_1 src1_sel:DWORD
	v_lshl_add_u64 v[24:25], s[36:37], 0, v[24:25]
	s_ashr_i32 s27, s26, 31
	v_add3_u32 v5, v9, v5, s87
	v_add3_u32 v7, v7, v8, s87
	v_lshl_add_u64 v[24:25], s[26:27], 1, v[24:25]
	v_mov_b32_e32 v161, v1
	v_and_b32_e32 v5, 0xffff0000, v5
	v_and_b32_e32 v7, 0xffff0000, v7
	v_add_u32_e32 v16, 0xc00, v18
	v_lshl_add_u64 v[24:25], v[24:25], 0, v[160:161]
	v_or_b32_sdwa v2, v23, v2 dst_sel:DWORD dst_unused:UNUSED_PAD src0_sel:DWORD src1_sel:WORD_1
	v_or_b32_sdwa v5, v5, v4 dst_sel:DWORD dst_unused:UNUSED_PAD src0_sel:DWORD src1_sel:WORD_1
	v_or_b32_sdwa v4, v7, v6 dst_sel:DWORD dst_unused:UNUSED_PAD src0_sel:DWORD src1_sel:WORD_1
	ds_read2_b32 v[14:15], v16 offset0:12 offset1:77
	ds_read2_b32 v[16:17], v16 offset0:142 offset1:207
	global_store_dwordx4 v[24:25], v[2:5], off sc1
	s_add_i32 s13, s13, s12
	s_cmpk_lt_i32 s13, 0x360
	s_waitcnt lgkmcnt(3)
	v_and_b32_sdwa v3, v10, v193 dst_sel:DWORD dst_unused:UNUSED_PAD src0_sel:WORD_1 src1_sel:DWORD
	v_add3_u32 v4, v10, v3, s87
	s_waitcnt lgkmcnt(2)
	v_and_b32_sdwa v3, v13, v193 dst_sel:DWORD dst_unused:UNUSED_PAD src0_sel:WORD_1 src1_sel:DWORD
	v_and_b32_sdwa v5, v11, v193 dst_sel:DWORD dst_unused:UNUSED_PAD src0_sel:WORD_1 src1_sel:DWORD
	v_and_b32_sdwa v2, v12, v193 dst_sel:DWORD dst_unused:UNUSED_PAD src0_sel:WORD_1 src1_sel:DWORD
	v_add3_u32 v3, v13, v3, s87
	v_add3_u32 v5, v11, v5, s87
	v_add3_u32 v2, v12, v2, s87
	v_and_b32_e32 v3, 0xffff0000, v3
	v_and_b32_e32 v5, 0xffff0000, v5
	v_or_b32_sdwa v3, v3, v2 dst_sel:DWORD dst_unused:UNUSED_PAD src0_sel:DWORD src1_sel:WORD_1
	v_or_b32_sdwa v2, v5, v4 dst_sel:DWORD dst_unused:UNUSED_PAD src0_sel:DWORD src1_sel:WORD_1
	s_waitcnt lgkmcnt(1)
	v_and_b32_sdwa v5, v14, v193 dst_sel:DWORD dst_unused:UNUSED_PAD src0_sel:WORD_1 src1_sel:DWORD
	v_add3_u32 v6, v14, v5, s87
	s_waitcnt lgkmcnt(0)
	v_and_b32_sdwa v5, v17, v193 dst_sel:DWORD dst_unused:UNUSED_PAD src0_sel:WORD_1 src1_sel:DWORD
	v_and_b32_sdwa v7, v15, v193 dst_sel:DWORD dst_unused:UNUSED_PAD src0_sel:WORD_1 src1_sel:DWORD
	v_and_b32_sdwa v4, v16, v193 dst_sel:DWORD dst_unused:UNUSED_PAD src0_sel:WORD_1 src1_sel:DWORD
	v_add3_u32 v5, v17, v5, s87
	v_add3_u32 v7, v15, v7, s87
	v_add3_u32 v4, v16, v4, s87
	v_and_b32_e32 v5, 0xffff0000, v5
	v_and_b32_e32 v7, 0xffff0000, v7
	v_or_b32_sdwa v5, v5, v4 dst_sel:DWORD dst_unused:UNUSED_PAD src0_sel:DWORD src1_sel:WORD_1
	v_or_b32_sdwa v4, v7, v6 dst_sel:DWORD dst_unused:UNUSED_PAD src0_sel:DWORD src1_sel:WORD_1
	global_store_dwordx4 v[24:25], v[2:5], off offset:16 sc1
	s_barrier
	s_cbranch_scc0 .LBB0_119

.LBB0_123:
	s_or_b64 exec, exec, s[34:35]
	s_waitcnt vmcnt(0)
	ds_write2_b32 v19, v2, v3 offset1:1
	ds_write2_b32 v19, v4, v5 offset0:2 offset1:3
	ds_write2_b32 v20, v6, v7 offset1:1
	ds_write2_b32 v20, v8, v9 offset0:2 offset1:3
	ds_write2_b32 v21, v10, v11 offset1:1
	ds_write2_b32 v21, v12, v13 offset0:2 offset1:3
	ds_write2_b32 v22, v14, v15 offset1:1
	ds_write2_b32 v22, v16, v17 offset0:2 offset1:3
	s_waitcnt lgkmcnt(0)
	s_barrier
	ds_read2_b32 v[2:3], v18 offset1:65
	ds_read2_b32 v[4:5], v18 offset0:130 offset1:195
	v_add_u32_e32 v8, 0x400, v18
	ds_read2_b32 v[6:7], v8 offset0:4 offset1:69
	ds_read2_b32 v[8:9], v8 offset0:134 offset1:199
	s_lshl_b64 s[26:27], s[26:27], 1
	s_waitcnt lgkmcnt(3)
	v_and_b32_sdwa v26, v2, v193 dst_sel:DWORD dst_unused:UNUSED_PAD src0_sel:WORD_1 src1_sel:DWORD
	s_waitcnt lgkmcnt(2)
	v_and_b32_sdwa v23, v4, v193 dst_sel:DWORD dst_unused:UNUSED_PAD src0_sel:WORD_1 src1_sel:DWORD
	v_add3_u32 v4, v4, v23, s87
	v_and_b32_sdwa v23, v5, v193 dst_sel:DWORD dst_unused:UNUSED_PAD src0_sel:WORD_1 src1_sel:DWORD
	v_add3_u32 v2, v2, v26, s87
	v_and_b32_sdwa v26, v3, v193 dst_sel:DWORD dst_unused:UNUSED_PAD src0_sel:WORD_1 src1_sel:DWORD
	v_add3_u32 v5, v5, v23, s87
	v_or_b32_e32 v24, s22, v147
	v_add3_u32 v3, v3, v26, s87
	v_and_b32_e32 v5, 0xffff0000, v5
	s_add_u32 s26, s9, s26
	v_add_u32_e32 v12, 0x800, v18
	v_ashrrev_i32_e32 v25, 31, v24
	v_and_b32_e32 v23, 0xffff0000, v3
	v_or_b32_sdwa v3, v5, v4 dst_sel:DWORD dst_unused:UNUSED_PAD src0_sel:DWORD src1_sel:WORD_1
	s_waitcnt lgkmcnt(0)
	v_and_b32_sdwa v4, v8, v193 dst_sel:DWORD dst_unused:UNUSED_PAD src0_sel:WORD_1 src1_sel:DWORD
	v_and_b32_sdwa v5, v6, v193 dst_sel:DWORD dst_unused:UNUSED_PAD src0_sel:WORD_1 src1_sel:DWORD
	s_addc_u32 s27, s12, s27
	ds_read2_b32 v[10:11], v12 offset0:8 offset1:73
	ds_read2_b32 v[12:13], v12 offset0:138 offset1:203
	v_lshlrev_b64 v[24:25], 11, v[24:25]
	v_add3_u32 v6, v6, v5, s87
	v_add3_u32 v4, v8, v4, s87
	v_and_b32_sdwa v5, v9, v193 dst_sel:DWORD dst_unused:UNUSED_PAD src0_sel:WORD_1 src1_sel:DWORD
	v_and_b32_sdwa v8, v7, v193 dst_sel:DWORD dst_unused:UNUSED_PAD src0_sel:WORD_1 src1_sel:DWORD
	v_lshl_add_u64 v[24:25], s[26:27], 0, v[24:25]
	s_ashr_i32 s1, s0, 31
	v_add3_u32 v5, v9, v5, s87
	v_add3_u32 v7, v7, v8, s87
	v_lshl_add_u64 v[24:25], s[0:1], 1, v[24:25]
	v_mov_b32_e32 v161, v1
	v_and_b32_e32 v5, 0xffff0000, v5
	v_and_b32_e32 v7, 0xffff0000, v7
	v_add_u32_e32 v16, 0xc00, v18
	v_lshl_add_u64 v[24:25], v[24:25], 0, v[160:161]
	v_or_b32_sdwa v2, v23, v2 dst_sel:DWORD dst_unused:UNUSED_PAD src0_sel:DWORD src1_sel:WORD_1
	v_or_b32_sdwa v5, v5, v4 dst_sel:DWORD dst_unused:UNUSED_PAD src0_sel:DWORD src1_sel:WORD_1
	v_or_b32_sdwa v4, v7, v6 dst_sel:DWORD dst_unused:UNUSED_PAD src0_sel:DWORD src1_sel:WORD_1
	ds_read2_b32 v[14:15], v16 offset0:12 offset1:77
	ds_read2_b32 v[16:17], v16 offset0:142 offset1:207
	global_store_dwordx4 v[24:25], v[2:5], off sc1
	s_add_i32 s6, s6, s8
	s_cmpk_gt_i32 s6, 0xff
	s_waitcnt lgkmcnt(3)
	v_and_b32_sdwa v3, v10, v193 dst_sel:DWORD dst_unused:UNUSED_PAD src0_sel:WORD_1 src1_sel:DWORD
	v_add3_u32 v4, v10, v3, s87
	s_waitcnt lgkmcnt(2)
	v_and_b32_sdwa v3, v13, v193 dst_sel:DWORD dst_unused:UNUSED_PAD src0_sel:WORD_1 src1_sel:DWORD
	v_and_b32_sdwa v5, v11, v193 dst_sel:DWORD dst_unused:UNUSED_PAD src0_sel:WORD_1 src1_sel:DWORD
	v_and_b32_sdwa v2, v12, v193 dst_sel:DWORD dst_unused:UNUSED_PAD src0_sel:WORD_1 src1_sel:DWORD
	v_add3_u32 v3, v13, v3, s87
	v_add3_u32 v5, v11, v5, s87
	v_add3_u32 v2, v12, v2, s87
	v_and_b32_e32 v3, 0xffff0000, v3
	v_and_b32_e32 v5, 0xffff0000, v5
	v_or_b32_sdwa v3, v3, v2 dst_sel:DWORD dst_unused:UNUSED_PAD src0_sel:DWORD src1_sel:WORD_1
	v_or_b32_sdwa v2, v5, v4 dst_sel:DWORD dst_unused:UNUSED_PAD src0_sel:DWORD src1_sel:WORD_1
	s_waitcnt lgkmcnt(1)
	v_and_b32_sdwa v5, v14, v193 dst_sel:DWORD dst_unused:UNUSED_PAD src0_sel:WORD_1 src1_sel:DWORD
	v_add3_u32 v6, v14, v5, s87
	s_waitcnt lgkmcnt(0)
	v_and_b32_sdwa v5, v17, v193 dst_sel:DWORD dst_unused:UNUSED_PAD src0_sel:WORD_1 src1_sel:DWORD
	v_and_b32_sdwa v7, v15, v193 dst_sel:DWORD dst_unused:UNUSED_PAD src0_sel:WORD_1 src1_sel:DWORD
	v_and_b32_sdwa v4, v16, v193 dst_sel:DWORD dst_unused:UNUSED_PAD src0_sel:WORD_1 src1_sel:DWORD
	v_add3_u32 v5, v17, v5, s87
	v_add3_u32 v7, v15, v7, s87
	v_add3_u32 v4, v16, v4, s87
	v_and_b32_e32 v5, 0xffff0000, v5
	v_and_b32_e32 v7, 0xffff0000, v7
	v_or_b32_sdwa v5, v5, v4 dst_sel:DWORD dst_unused:UNUSED_PAD src0_sel:DWORD src1_sel:WORD_1
	v_or_b32_sdwa v4, v7, v6 dst_sel:DWORD dst_unused:UNUSED_PAD src0_sel:DWORD src1_sel:WORD_1
	global_store_dwordx4 v[24:25], v[2:5], off offset:16 sc1
	s_barrier
	s_cbranch_scc1 .LBB0_126

.LBB0_399:
	s_or_b64 exec, exec, s[0:1]
	v_lshl_add_u64 v[28:29], v[16:17], 0, v[0:1]
	global_load_dwordx4 v[16:19], v[28:29], off
	v_lshrrev_b32_e32 v9, 10, v14
	v_add_u32_e32 v9, 1, v9
	v_mov_b64_e32 v[14:15], s[26:27]
	v_cndmask_b32_e64 v9, v9, 0, vcc
	v_mad_u64_u32 v[14:15], s[0:1], v9, s33, v[14:15]
	v_lshlrev_b64 v[20:21], 12, v[2:3]
	s_mov_b64 s[0:1], 0x1000
	v_lshl_add_u64 v[30:31], v[4:5], 0, v[20:21]
	v_lshl_add_u64 v[32:33], v[14:15], 0, s[0:1]
	v_lshl_add_u64 v[20:21], v[32:33], 0, v[0:1]
	v_lshl_add_u64 v[34:35], v[14:15], 0, v[0:1]
	v_lshlrev_b64 v[14:15], 11, v[2:3]
	v_lshl_add_u64 v[36:37], v[6:7], 0, v[14:15]
	v_add_u32_e32 v2, s6, v2
	s_movk_i32 s0, 0x17ff
	v_cmp_lt_i32_e32 vcc, s0, v2
	s_or_b64 s[34:35], vcc, s[34:35]
	s_waitcnt vmcnt(0)
	global_store_dwordx4 v[30:31], v[16:19], off sc1
	global_load_dwordx4 v[20:23], v[20:21], off
	v_mov_b32_e32 v14, v16
	global_load_dwordx4 v[24:27], v[34:35], off
	v_mov_b32_e32 v15, v18
	v_mov_b32_e32 v18, v17
	s_waitcnt vmcnt(1)
	v_mov_b32_e32 v16, v20
	v_mov_b32_e32 v17, v22
	v_mov_b32_e32 v22, v21
	s_waitcnt vmcnt(0)
	v_mov_b32_e32 v38, v24
	v_mov_b32_e32 v39, v26
	v_mov_b32_e32 v26, v25
	v_pk_add_f32 v[16:17], v[16:17], 1.0 op_sel_hi:[1,0]
	v_pk_add_f32 v[20:21], v[22:23], 1.0 op_sel_hi:[1,0]
	v_pk_fma_f32 v[14:15], v[14:15], v[16:17], v[38:39]
	v_pk_fma_f32 v[16:17], v[18:19], v[20:21], v[26:27]
	v_and_b32_sdwa v3, v15, v193 dst_sel:DWORD dst_unused:UNUSED_PAD src0_sel:WORD_1 src1_sel:DWORD
	v_and_b32_sdwa v11, v17, v193 dst_sel:DWORD dst_unused:UNUSED_PAD src0_sel:WORD_1 src1_sel:DWORD
	v_and_b32_sdwa v13, v16, v193 dst_sel:DWORD dst_unused:UNUSED_PAD src0_sel:WORD_1 src1_sel:DWORD
	v_and_b32_sdwa v9, v14, v193 dst_sel:DWORD dst_unused:UNUSED_PAD src0_sel:WORD_1 src1_sel:DWORD
	v_add3_u32 v11, v17, v11, s87
	v_add3_u32 v13, v16, v13, s87
	v_add3_u32 v9, v14, v9, s87
	v_add3_u32 v3, v15, v3, s87
	v_and_b32_e32 v11, 0xffff0000, v11
	v_and_b32_e32 v13, 0xffff0000, v13
	v_or_b32_sdwa v15, v11, v3 dst_sel:DWORD dst_unused:UNUSED_PAD src0_sel:DWORD src1_sel:WORD_1
	v_or_b32_sdwa v14, v13, v9 dst_sel:DWORD dst_unused:UNUSED_PAD src0_sel:DWORD src1_sel:WORD_1
	global_store_dwordx2 v[36:37], v[14:15], off
	global_load_dwordx4 v[14:17], v[28:29], off offset:1024
	v_mov_b32_e32 v9, v1
	v_lshl_add_u64 v[18:19], v[32:33], 0, v[8:9]
	s_waitcnt vmcnt(0)
	global_store_dwordx4 v[30:31], v[14:17], off offset:1024 sc1
	global_load_dwordx4 v[18:21], v[18:19], off
	s_nop 0
	global_load_dwordx4 v[22:25], v[34:35], off offset:1024
	v_mov_b32_e32 v27, v16
	v_mov_b32_e32 v16, v15
	v_mov_b32_e32 v26, v14
	s_waitcnt vmcnt(1)
	v_mov_b32_e32 v15, v20
	v_mov_b32_e32 v20, v19
	v_mov_b32_e32 v14, v18
	s_waitcnt vmcnt(0)
	v_mov_b32_e32 v39, v24
	v_mov_b32_e32 v24, v23
	v_pk_add_f32 v[18:19], v[20:21], 1.0 op_sel_hi:[1,0]
	v_mov_b32_e32 v38, v22
	v_pk_add_f32 v[14:15], v[14:15], 1.0 op_sel_hi:[1,0]
	v_pk_fma_f32 v[16:17], v[16:17], v[18:19], v[24:25]
	v_pk_fma_f32 v[14:15], v[26:27], v[14:15], v[38:39]
	v_and_b32_sdwa v11, v17, v193 dst_sel:DWORD dst_unused:UNUSED_PAD src0_sel:WORD_1 src1_sel:DWORD
	v_and_b32_sdwa v13, v16, v193 dst_sel:DWORD dst_unused:UNUSED_PAD src0_sel:WORD_1 src1_sel:DWORD
	v_and_b32_sdwa v3, v15, v193 dst_sel:DWORD dst_unused:UNUSED_PAD src0_sel:WORD_1 src1_sel:DWORD
	v_and_b32_sdwa v9, v14, v193 dst_sel:DWORD dst_unused:UNUSED_PAD src0_sel:WORD_1 src1_sel:DWORD
	v_add3_u32 v11, v17, v11, s87
	v_add3_u32 v13, v16, v13, s87
	v_add3_u32 v9, v14, v9, s87
	v_add3_u32 v3, v15, v3, s87
	v_and_b32_e32 v11, 0xffff0000, v11
	v_and_b32_e32 v13, 0xffff0000, v13
	v_or_b32_sdwa v15, v11, v3 dst_sel:DWORD dst_unused:UNUSED_PAD src0_sel:DWORD src1_sel:WORD_1
	v_or_b32_sdwa v14, v13, v9 dst_sel:DWORD dst_unused:UNUSED_PAD src0_sel:DWORD src1_sel:WORD_1
	global_store_dwordx2 v[36:37], v[14:15], off offset:512
	global_load_dwordx4 v[14:17], v[28:29], off offset:2048
	v_mov_b32_e32 v11, v1
	v_lshl_add_u64 v[18:19], v[32:33], 0, v[10:11]
	s_waitcnt vmcnt(0)
	global_store_dwordx4 v[30:31], v[14:17], off offset:2048 sc1
	global_load_dwordx4 v[18:21], v[18:19], off
	s_nop 0
	global_load_dwordx4 v[22:25], v[34:35], off offset:2048
	v_mov_b32_e32 v27, v16
	v_mov_b32_e32 v16, v15
	v_mov_b32_e32 v26, v14
	s_waitcnt vmcnt(1)
	v_mov_b32_e32 v15, v20
	v_mov_b32_e32 v20, v19
	v_mov_b32_e32 v14, v18
	s_waitcnt vmcnt(0)
	v_mov_b32_e32 v39, v24
	v_mov_b32_e32 v24, v23
	v_pk_add_f32 v[18:19], v[20:21], 1.0 op_sel_hi:[1,0]
	v_mov_b32_e32 v38, v22
	v_pk_add_f32 v[14:15], v[14:15], 1.0 op_sel_hi:[1,0]
	v_pk_fma_f32 v[16:17], v[16:17], v[18:19], v[24:25]
	v_pk_fma_f32 v[14:15], v[26:27], v[14:15], v[38:39]
	v_and_b32_sdwa v11, v17, v193 dst_sel:DWORD dst_unused:UNUSED_PAD src0_sel:WORD_1 src1_sel:DWORD
	v_and_b32_sdwa v13, v16, v193 dst_sel:DWORD dst_unused:UNUSED_PAD src0_sel:WORD_1 src1_sel:DWORD
	v_and_b32_sdwa v3, v15, v193 dst_sel:DWORD dst_unused:UNUSED_PAD src0_sel:WORD_1 src1_sel:DWORD
	v_and_b32_sdwa v9, v14, v193 dst_sel:DWORD dst_unused:UNUSED_PAD src0_sel:WORD_1 src1_sel:DWORD
	v_add3_u32 v11, v17, v11, s87
	v_add3_u32 v13, v16, v13, s87
	v_add3_u32 v9, v14, v9, s87
	v_add3_u32 v3, v15, v3, s87
	v_and_b32_e32 v11, 0xffff0000, v11
	v_and_b32_e32 v13, 0xffff0000, v13
	v_or_b32_sdwa v15, v11, v3 dst_sel:DWORD dst_unused:UNUSED_PAD src0_sel:DWORD src1_sel:WORD_1
	v_or_b32_sdwa v14, v13, v9 dst_sel:DWORD dst_unused:UNUSED_PAD src0_sel:DWORD src1_sel:WORD_1
	global_store_dwordx2 v[36:37], v[14:15], off offset:1024
	global_load_dwordx4 v[14:17], v[28:29], off offset:3072
	v_mov_b32_e32 v13, v1
	v_lshl_add_u64 v[18:19], v[32:33], 0, v[12:13]
	s_waitcnt vmcnt(0)
	global_store_dwordx4 v[30:31], v[14:17], off offset:3072 sc1
	global_load_dwordx4 v[18:21], v[18:19], off
	s_nop 0
	global_load_dwordx4 v[22:25], v[34:35], off offset:3072
	v_mov_b32_e32 v27, v16
	v_mov_b32_e32 v16, v15
	v_mov_b32_e32 v26, v14
	s_waitcnt vmcnt(1)
	v_mov_b32_e32 v15, v20
	v_mov_b32_e32 v20, v19
	v_mov_b32_e32 v14, v18
	s_waitcnt vmcnt(0)
	v_mov_b32_e32 v29, v24
	v_mov_b32_e32 v24, v23
	v_pk_add_f32 v[18:19], v[20:21], 1.0 op_sel_hi:[1,0]
	v_mov_b32_e32 v28, v22
	v_pk_add_f32 v[14:15], v[14:15], 1.0 op_sel_hi:[1,0]
	v_pk_fma_f32 v[16:17], v[16:17], v[18:19], v[24:25]
	v_pk_fma_f32 v[14:15], v[26:27], v[14:15], v[28:29]
	v_and_b32_sdwa v11, v17, v193 dst_sel:DWORD dst_unused:UNUSED_PAD src0_sel:WORD_1 src1_sel:DWORD
	v_and_b32_sdwa v13, v16, v193 dst_sel:DWORD dst_unused:UNUSED_PAD src0_sel:WORD_1 src1_sel:DWORD
	v_and_b32_sdwa v3, v15, v193 dst_sel:DWORD dst_unused:UNUSED_PAD src0_sel:WORD_1 src1_sel:DWORD
	v_and_b32_sdwa v9, v14, v193 dst_sel:DWORD dst_unused:UNUSED_PAD src0_sel:WORD_1 src1_sel:DWORD
	v_add3_u32 v11, v17, v11, s87
	v_add3_u32 v13, v16, v13, s87
	v_add3_u32 v9, v14, v9, s87
	v_add3_u32 v3, v15, v3, s87
	v_and_b32_e32 v11, 0xffff0000, v11
	v_and_b32_e32 v13, 0xffff0000, v13
	v_or_b32_sdwa v15, v11, v3 dst_sel:DWORD dst_unused:UNUSED_PAD src0_sel:DWORD src1_sel:WORD_1
	v_or_b32_sdwa v14, v13, v9 dst_sel:DWORD dst_unused:UNUSED_PAD src0_sel:DWORD src1_sel:WORD_1
	global_store_dwordx2 v[36:37], v[14:15], off offset:1536
	s_andn2_b64 exec, exec, s[34:35]
	s_cbranch_execz .LBB0_404

.LBB0_439:
	s_or_b64 exec, exec, s[38:39]
	s_waitcnt vmcnt(3)
	ds_write2_b32 v19, v2, v3 offset1:1
	ds_write2_b32 v19, v4, v5 offset0:2 offset1:3
	s_waitcnt vmcnt(2)
	ds_write2_b32 v20, v6, v7 offset1:1
	ds_write2_b32 v20, v8, v9 offset0:2 offset1:3
	s_waitcnt vmcnt(1)
	ds_write2_b32 v21, v10, v11 offset1:1
	ds_write2_b32 v21, v12, v13 offset0:2 offset1:3
	s_waitcnt vmcnt(0)
	ds_write2_b32 v22, v14, v15 offset1:1
	ds_write2_b32 v22, v16, v17 offset0:2 offset1:3
	s_waitcnt lgkmcnt(0)
	s_barrier
	ds_read2_b32 v[2:3], v18 offset1:65
	ds_read2_b32 v[4:5], v18 offset0:130 offset1:195
	v_add_u32_e32 v8, 0x400, v18
	ds_read2_b32 v[6:7], v8 offset0:4 offset1:69
	ds_read2_b32 v[8:9], v8 offset0:134 offset1:199
	s_lshl_b64 s[36:37], s[36:37], 1
	s_waitcnt lgkmcnt(3)
	v_and_b32_sdwa v26, v2, v193 dst_sel:DWORD dst_unused:UNUSED_PAD src0_sel:WORD_1 src1_sel:DWORD
	s_waitcnt lgkmcnt(2)
	v_and_b32_sdwa v23, v4, v193 dst_sel:DWORD dst_unused:UNUSED_PAD src0_sel:WORD_1 src1_sel:DWORD
	v_add3_u32 v4, v4, v23, s87
	v_and_b32_sdwa v23, v5, v193 dst_sel:DWORD dst_unused:UNUSED_PAD src0_sel:WORD_1 src1_sel:DWORD
	v_add3_u32 v2, v2, v26, s87
	v_and_b32_sdwa v26, v3, v193 dst_sel:DWORD dst_unused:UNUSED_PAD src0_sel:WORD_1 src1_sel:DWORD
	v_add3_u32 v5, v5, v23, s87
	v_or_b32_e32 v24, s34, v147
	v_add3_u32 v3, v3, v26, s87
	v_and_b32_e32 v5, 0xffff0000, v5
	s_add_u32 s36, s13, s36
	v_add_u32_e32 v12, 0x800, v18
	v_ashrrev_i32_e32 v25, 31, v24
	v_and_b32_e32 v23, 0xffff0000, v3
	v_or_b32_sdwa v3, v5, v4 dst_sel:DWORD dst_unused:UNUSED_PAD src0_sel:DWORD src1_sel:WORD_1
	s_waitcnt lgkmcnt(0)
	v_and_b32_sdwa v4, v8, v193 dst_sel:DWORD dst_unused:UNUSED_PAD src0_sel:WORD_1 src1_sel:DWORD
	v_and_b32_sdwa v5, v6, v193 dst_sel:DWORD dst_unused:UNUSED_PAD src0_sel:WORD_1 src1_sel:DWORD
	s_addc_u32 s37, s14, s37
	ds_read2_b32 v[10:11], v12 offset0:8 offset1:73
	ds_read2_b32 v[12:13], v12 offset0:138 offset1:203
	v_lshlrev_b64 v[24:25], 11, v[24:25]
	v_add3_u32 v6, v6, v5, s87
	v_add3_u32 v4, v8, v4, s87
	v_and_b32_sdwa v5, v9, v193 dst_sel:DWORD dst_unused:UNUSED_PAD src0_sel:WORD_1 src1_sel:DWORD
	v_and_b32_sdwa v8, v7, v193 dst_sel:DWORD dst_unused:UNUSED_PAD src0_sel:WORD_1 src1_sel:DWORD
	v_lshl_add_u64 v[24:25], s[36:37], 0, v[24:25]
	s_ashr_i32 s27, s26, 31
	v_add3_u32 v5, v9, v5, s87
	v_add3_u32 v7, v7, v8, s87
	v_lshl_add_u64 v[24:25], s[26:27], 1, v[24:25]
	v_mov_b32_e32 v161, v1
	v_and_b32_e32 v5, 0xffff0000, v5
	v_and_b32_e32 v7, 0xffff0000, v7
	v_add_u32_e32 v16, 0xc00, v18
	v_lshl_add_u64 v[24:25], v[24:25], 0, v[160:161]
	v_or_b32_sdwa v2, v23, v2 dst_sel:DWORD dst_unused:UNUSED_PAD src0_sel:DWORD src1_sel:WORD_1
	v_or_b32_sdwa v5, v5, v4 dst_sel:DWORD dst_unused:UNUSED_PAD src0_sel:DWORD src1_sel:WORD_1
	v_or_b32_sdwa v4, v7, v6 dst_sel:DWORD dst_unused:UNUSED_PAD src0_sel:DWORD src1_sel:WORD_1
	ds_read2_b32 v[14:15], v16 offset0:12 offset1:77
	ds_read2_b32 v[16:17], v16 offset0:142 offset1:207
	global_store_dwordx4 v[24:25], v[2:5], off sc1
	s_add_i32 s12, s12, s11
	s_cmpk_lt_i32 s12, 0x400
	s_waitcnt lgkmcnt(3)
	v_and_b32_sdwa v3, v10, v193 dst_sel:DWORD dst_unused:UNUSED_PAD src0_sel:WORD_1 src1_sel:DWORD
	v_add3_u32 v4, v10, v3, s87
	s_waitcnt lgkmcnt(2)
	v_and_b32_sdwa v3, v13, v193 dst_sel:DWORD dst_unused:UNUSED_PAD src0_sel:WORD_1 src1_sel:DWORD
	v_and_b32_sdwa v5, v11, v193 dst_sel:DWORD dst_unused:UNUSED_PAD src0_sel:WORD_1 src1_sel:DWORD
	v_and_b32_sdwa v2, v12, v193 dst_sel:DWORD dst_unused:UNUSED_PAD src0_sel:WORD_1 src1_sel:DWORD
	v_add3_u32 v3, v13, v3, s87
	v_add3_u32 v5, v11, v5, s87
	v_add3_u32 v2, v12, v2, s87
	v_and_b32_e32 v3, 0xffff0000, v3
	v_and_b32_e32 v5, 0xffff0000, v5
	v_or_b32_sdwa v3, v3, v2 dst_sel:DWORD dst_unused:UNUSED_PAD src0_sel:DWORD src1_sel:WORD_1
	v_or_b32_sdwa v2, v5, v4 dst_sel:DWORD dst_unused:UNUSED_PAD src0_sel:DWORD src1_sel:WORD_1
	s_waitcnt lgkmcnt(1)
	v_and_b32_sdwa v5, v14, v193 dst_sel:DWORD dst_unused:UNUSED_PAD src0_sel:WORD_1 src1_sel:DWORD
	v_add3_u32 v6, v14, v5, s87
	s_waitcnt lgkmcnt(0)
	v_and_b32_sdwa v5, v17, v193 dst_sel:DWORD dst_unused:UNUSED_PAD src0_sel:WORD_1 src1_sel:DWORD
	v_and_b32_sdwa v7, v15, v193 dst_sel:DWORD dst_unused:UNUSED_PAD src0_sel:WORD_1 src1_sel:DWORD
	v_and_b32_sdwa v4, v16, v193 dst_sel:DWORD dst_unused:UNUSED_PAD src0_sel:WORD_1 src1_sel:DWORD
	v_add3_u32 v5, v17, v5, s87
	v_add3_u32 v7, v15, v7, s87
	v_add3_u32 v4, v16, v4, s87
	v_and_b32_e32 v5, 0xffff0000, v5
	v_and_b32_e32 v7, 0xffff0000, v7
	v_or_b32_sdwa v5, v5, v4 dst_sel:DWORD dst_unused:UNUSED_PAD src0_sel:DWORD src1_sel:WORD_1
	v_or_b32_sdwa v4, v7, v6 dst_sel:DWORD dst_unused:UNUSED_PAD src0_sel:DWORD src1_sel:WORD_1
	global_store_dwordx4 v[24:25], v[2:5], off offset:16 sc1
	s_barrier
	s_cbranch_scc0 .LBB0_442

.LBB0_446:
	s_or_b64 exec, exec, s[34:35]
	s_waitcnt vmcnt(3)
	ds_write2_b32 v19, v2, v3 offset1:1
	ds_write2_b32 v19, v4, v5 offset0:2 offset1:3
	s_waitcnt vmcnt(2)
	ds_write2_b32 v20, v6, v7 offset1:1
	ds_write2_b32 v20, v8, v9 offset0:2 offset1:3
	s_waitcnt vmcnt(1)
	ds_write2_b32 v21, v10, v11 offset1:1
	ds_write2_b32 v21, v12, v13 offset0:2 offset1:3
	s_waitcnt vmcnt(0)
	ds_write2_b32 v22, v14, v15 offset1:1
	ds_write2_b32 v22, v16, v17 offset0:2 offset1:3
	s_waitcnt lgkmcnt(0)
	s_barrier
	ds_read2_b32 v[2:3], v18 offset1:65
	ds_read2_b32 v[4:5], v18 offset0:130 offset1:195
	v_add_u32_e32 v8, 0x400, v18
	ds_read2_b32 v[6:7], v8 offset0:4 offset1:69
	ds_read2_b32 v[8:9], v8 offset0:134 offset1:199
	s_lshl_b64 s[26:27], s[26:27], 1
	s_waitcnt lgkmcnt(3)
	v_and_b32_sdwa v26, v2, v193 dst_sel:DWORD dst_unused:UNUSED_PAD src0_sel:WORD_1 src1_sel:DWORD
	s_waitcnt lgkmcnt(2)
	v_and_b32_sdwa v23, v4, v193 dst_sel:DWORD dst_unused:UNUSED_PAD src0_sel:WORD_1 src1_sel:DWORD
	v_add3_u32 v4, v4, v23, s87
	v_and_b32_sdwa v23, v5, v193 dst_sel:DWORD dst_unused:UNUSED_PAD src0_sel:WORD_1 src1_sel:DWORD
	v_add3_u32 v2, v2, v26, s87
	v_and_b32_sdwa v26, v3, v193 dst_sel:DWORD dst_unused:UNUSED_PAD src0_sel:WORD_1 src1_sel:DWORD
	v_add3_u32 v5, v5, v23, s87
	v_or_b32_e32 v24, s22, v147
	v_add3_u32 v3, v3, v26, s87
	v_and_b32_e32 v5, 0xffff0000, v5
	s_add_u32 s26, s8, s26
	v_add_u32_e32 v12, 0x800, v18
	v_ashrrev_i32_e32 v25, 31, v24
	v_and_b32_e32 v23, 0xffff0000, v3
	v_or_b32_sdwa v3, v5, v4 dst_sel:DWORD dst_unused:UNUSED_PAD src0_sel:DWORD src1_sel:WORD_1
	s_waitcnt lgkmcnt(0)
	v_and_b32_sdwa v4, v8, v193 dst_sel:DWORD dst_unused:UNUSED_PAD src0_sel:WORD_1 src1_sel:DWORD
	v_and_b32_sdwa v5, v6, v193 dst_sel:DWORD dst_unused:UNUSED_PAD src0_sel:WORD_1 src1_sel:DWORD
	s_addc_u32 s27, s11, s27
	ds_read2_b32 v[10:11], v12 offset0:8 offset1:73
	ds_read2_b32 v[12:13], v12 offset0:138 offset1:203
	v_lshlrev_b64 v[24:25], 13, v[24:25]
	v_add3_u32 v6, v6, v5, s87
	v_add3_u32 v4, v8, v4, s87
	v_and_b32_sdwa v5, v9, v193 dst_sel:DWORD dst_unused:UNUSED_PAD src0_sel:WORD_1 src1_sel:DWORD
	v_and_b32_sdwa v8, v7, v193 dst_sel:DWORD dst_unused:UNUSED_PAD src0_sel:WORD_1 src1_sel:DWORD
	v_lshl_add_u64 v[24:25], s[26:27], 0, v[24:25]
	s_ashr_i32 s1, s0, 31
	v_add3_u32 v5, v9, v5, s87
	v_add3_u32 v7, v7, v8, s87
	v_lshl_add_u64 v[24:25], s[0:1], 1, v[24:25]
	v_mov_b32_e32 v161, v1
	v_and_b32_e32 v5, 0xffff0000, v5
	v_and_b32_e32 v7, 0xffff0000, v7
	v_add_u32_e32 v16, 0xc00, v18
	v_lshl_add_u64 v[24:25], v[24:25], 0, v[160:161]
	v_or_b32_sdwa v2, v23, v2 dst_sel:DWORD dst_unused:UNUSED_PAD src0_sel:DWORD src1_sel:WORD_1
	v_or_b32_sdwa v5, v5, v4 dst_sel:DWORD dst_unused:UNUSED_PAD src0_sel:DWORD src1_sel:WORD_1
	v_or_b32_sdwa v4, v7, v6 dst_sel:DWORD dst_unused:UNUSED_PAD src0_sel:DWORD src1_sel:WORD_1
	ds_read2_b32 v[14:15], v16 offset0:12 offset1:77
	ds_read2_b32 v[16:17], v16 offset0:142 offset1:207
	global_store_dwordx4 v[24:25], v[2:5], off sc1
	s_add_i32 s5, s5, s6
	s_cmpk_gt_i32 s5, 0x3ff
	s_waitcnt lgkmcnt(3)
	v_and_b32_sdwa v3, v10, v193 dst_sel:DWORD dst_unused:UNUSED_PAD src0_sel:WORD_1 src1_sel:DWORD
	v_add3_u32 v4, v10, v3, s87
	s_waitcnt lgkmcnt(2)
	v_and_b32_sdwa v3, v13, v193 dst_sel:DWORD dst_unused:UNUSED_PAD src0_sel:WORD_1 src1_sel:DWORD
	v_and_b32_sdwa v5, v11, v193 dst_sel:DWORD dst_unused:UNUSED_PAD src0_sel:WORD_1 src1_sel:DWORD
	v_and_b32_sdwa v2, v12, v193 dst_sel:DWORD dst_unused:UNUSED_PAD src0_sel:WORD_1 src1_sel:DWORD
	v_add3_u32 v3, v13, v3, s87
	v_add3_u32 v5, v11, v5, s87
	v_add3_u32 v2, v12, v2, s87
	v_and_b32_e32 v3, 0xffff0000, v3
	v_and_b32_e32 v5, 0xffff0000, v5
	v_or_b32_sdwa v3, v3, v2 dst_sel:DWORD dst_unused:UNUSED_PAD src0_sel:DWORD src1_sel:WORD_1
	v_or_b32_sdwa v2, v5, v4 dst_sel:DWORD dst_unused:UNUSED_PAD src0_sel:DWORD src1_sel:WORD_1
	s_waitcnt lgkmcnt(1)
	v_and_b32_sdwa v5, v14, v193 dst_sel:DWORD dst_unused:UNUSED_PAD src0_sel:WORD_1 src1_sel:DWORD
	v_add3_u32 v6, v14, v5, s87
	s_waitcnt lgkmcnt(0)
	v_and_b32_sdwa v5, v17, v193 dst_sel:DWORD dst_unused:UNUSED_PAD src0_sel:WORD_1 src1_sel:DWORD
	v_and_b32_sdwa v7, v15, v193 dst_sel:DWORD dst_unused:UNUSED_PAD src0_sel:WORD_1 src1_sel:DWORD
	v_and_b32_sdwa v4, v16, v193 dst_sel:DWORD dst_unused:UNUSED_PAD src0_sel:WORD_1 src1_sel:DWORD
	v_add3_u32 v5, v17, v5, s87
	v_add3_u32 v7, v15, v7, s87
	v_add3_u32 v4, v16, v4, s87
	v_and_b32_e32 v5, 0xffff0000, v5
	v_and_b32_e32 v7, 0xffff0000, v7
	v_or_b32_sdwa v5, v5, v4 dst_sel:DWORD dst_unused:UNUSED_PAD src0_sel:DWORD src1_sel:WORD_1
	v_or_b32_sdwa v4, v7, v6 dst_sel:DWORD dst_unused:UNUSED_PAD src0_sel:DWORD src1_sel:WORD_1
	global_store_dwordx4 v[24:25], v[2:5], off offset:16 sc1
	s_barrier
	s_cbranch_scc1 .LBB0_449

.LBB0_480:
	s_or_b64 exec, exec, s[26:27]
	s_waitcnt vmcnt(3)
	ds_write2_b32 v0, v2, v3 offset1:1
	ds_write2_b32 v0, v4, v5 offset0:2 offset1:3
	s_waitcnt vmcnt(2)
	ds_write2_b32 v21, v6, v7 offset1:1
	ds_write2_b32 v21, v8, v9 offset0:2 offset1:3
	s_waitcnt vmcnt(1)
	ds_write2_b32 v22, v10, v11 offset1:1
	ds_write2_b32 v22, v12, v13 offset0:2 offset1:3
	s_waitcnt vmcnt(0)
	ds_write2_b32 v23, v14, v15 offset1:1
	ds_write2_b32 v23, v16, v17 offset0:2 offset1:3
	s_waitcnt lgkmcnt(0)
	s_barrier
	ds_read2_b32 v[2:3], v20 offset1:65
	ds_read2_b32 v[4:5], v20 offset0:130 offset1:195
	v_add_u32_e32 v8, 0x400, v20
	ds_read2_b32 v[6:7], v8 offset0:4 offset1:69
	ds_read2_b32 v[8:9], v8 offset0:134 offset1:199
	s_mul_hi_i32 s9, s1, 0x6c0000
	s_waitcnt lgkmcnt(3)
	v_and_b32_sdwa v26, v2, v193 dst_sel:DWORD dst_unused:UNUSED_PAD src0_sel:WORD_1 src1_sel:DWORD
	s_waitcnt lgkmcnt(2)
	v_and_b32_sdwa v19, v4, v193 dst_sel:DWORD dst_unused:UNUSED_PAD src0_sel:WORD_1 src1_sel:DWORD
	v_add3_u32 v4, v4, v19, s87
	v_and_b32_sdwa v19, v5, v193 dst_sel:DWORD dst_unused:UNUSED_PAD src0_sel:WORD_1 src1_sel:DWORD
	v_add3_u32 v2, v2, v26, s87
	v_and_b32_sdwa v26, v3, v193 dst_sel:DWORD dst_unused:UNUSED_PAD src0_sel:WORD_1 src1_sel:DWORD
	v_add3_u32 v5, v5, v19, s87
	s_mul_i32 s1, s1, 0x6c0000
	v_or_b32_e32 v24, s22, v147
	v_add3_u32 v3, v3, v26, s87
	v_and_b32_e32 v5, 0xffff0000, v5
	s_add_u32 s12, s46, s1
	v_add_u32_e32 v12, 0x800, v20
	v_ashrrev_i32_e32 v25, 31, v24
	v_and_b32_e32 v19, 0xffff0000, v3
	v_or_b32_sdwa v3, v5, v4 dst_sel:DWORD dst_unused:UNUSED_PAD src0_sel:DWORD src1_sel:WORD_1
	s_waitcnt lgkmcnt(0)
	v_and_b32_sdwa v4, v8, v193 dst_sel:DWORD dst_unused:UNUSED_PAD src0_sel:WORD_1 src1_sel:DWORD
	v_and_b32_sdwa v5, v6, v193 dst_sel:DWORD dst_unused:UNUSED_PAD src0_sel:WORD_1 src1_sel:DWORD
	s_addc_u32 s13, s47, s9
	ds_read2_b32 v[10:11], v12 offset0:8 offset1:73
	ds_read2_b32 v[12:13], v12 offset0:138 offset1:203
	v_lshlrev_b64 v[24:25], 11, v[24:25]
	v_add3_u32 v6, v6, v5, s87
	v_add3_u32 v4, v8, v4, s87
	v_and_b32_sdwa v5, v9, v193 dst_sel:DWORD dst_unused:UNUSED_PAD src0_sel:WORD_1 src1_sel:DWORD
	v_and_b32_sdwa v8, v7, v193 dst_sel:DWORD dst_unused:UNUSED_PAD src0_sel:WORD_1 src1_sel:DWORD
	v_lshl_add_u64 v[24:25], s[12:13], 0, v[24:25]
	s_ashr_i32 s1, s0, 31
	v_add3_u32 v5, v9, v5, s87
	v_add3_u32 v7, v7, v8, s87
	v_lshl_add_u64 v[24:25], s[0:1], 1, v[24:25]
	v_mov_b32_e32 v161, v1
	v_and_b32_e32 v5, 0xffff0000, v5
	v_and_b32_e32 v7, 0xffff0000, v7
	v_add_u32_e32 v16, 0xc00, v20
	v_lshl_add_u64 v[24:25], v[24:25], 0, v[160:161]
	v_or_b32_sdwa v2, v19, v2 dst_sel:DWORD dst_unused:UNUSED_PAD src0_sel:DWORD src1_sel:WORD_1
	v_or_b32_sdwa v5, v5, v4 dst_sel:DWORD dst_unused:UNUSED_PAD src0_sel:DWORD src1_sel:WORD_1
	v_or_b32_sdwa v4, v7, v6 dst_sel:DWORD dst_unused:UNUSED_PAD src0_sel:DWORD src1_sel:WORD_1
	ds_read2_b32 v[14:15], v16 offset0:12 offset1:77
	ds_read2_b32 v[16:17], v16 offset0:142 offset1:207
	global_store_dwordx4 v[24:25], v[2:5], off sc1
	s_add_i32 s8, s8, s44
	s_cmpk_lt_i32 s8, 0x360
	s_waitcnt lgkmcnt(3)
	v_and_b32_sdwa v3, v10, v193 dst_sel:DWORD dst_unused:UNUSED_PAD src0_sel:WORD_1 src1_sel:DWORD
	v_add3_u32 v4, v10, v3, s87
	s_waitcnt lgkmcnt(2)
	v_and_b32_sdwa v3, v13, v193 dst_sel:DWORD dst_unused:UNUSED_PAD src0_sel:WORD_1 src1_sel:DWORD
	v_and_b32_sdwa v5, v11, v193 dst_sel:DWORD dst_unused:UNUSED_PAD src0_sel:WORD_1 src1_sel:DWORD
	v_and_b32_sdwa v2, v12, v193 dst_sel:DWORD dst_unused:UNUSED_PAD src0_sel:WORD_1 src1_sel:DWORD
	v_add3_u32 v3, v13, v3, s87
	v_add3_u32 v5, v11, v5, s87
	v_add3_u32 v2, v12, v2, s87
	v_and_b32_e32 v3, 0xffff0000, v3
	v_and_b32_e32 v5, 0xffff0000, v5
	v_or_b32_sdwa v3, v3, v2 dst_sel:DWORD dst_unused:UNUSED_PAD src0_sel:DWORD src1_sel:WORD_1
	v_or_b32_sdwa v2, v5, v4 dst_sel:DWORD dst_unused:UNUSED_PAD src0_sel:DWORD src1_sel:WORD_1
	s_waitcnt lgkmcnt(1)
	v_and_b32_sdwa v5, v14, v193 dst_sel:DWORD dst_unused:UNUSED_PAD src0_sel:WORD_1 src1_sel:DWORD
	v_add3_u32 v6, v14, v5, s87
	s_waitcnt lgkmcnt(0)
	v_and_b32_sdwa v5, v17, v193 dst_sel:DWORD dst_unused:UNUSED_PAD src0_sel:WORD_1 src1_sel:DWORD
	v_and_b32_sdwa v7, v15, v193 dst_sel:DWORD dst_unused:UNUSED_PAD src0_sel:WORD_1 src1_sel:DWORD
	v_and_b32_sdwa v4, v16, v193 dst_sel:DWORD dst_unused:UNUSED_PAD src0_sel:WORD_1 src1_sel:DWORD
	v_add3_u32 v5, v17, v5, s87
	v_add3_u32 v7, v15, v7, s87
	v_add3_u32 v4, v16, v4, s87
	v_and_b32_e32 v5, 0xffff0000, v5
	v_and_b32_e32 v7, 0xffff0000, v7
	v_or_b32_sdwa v5, v5, v4 dst_sel:DWORD dst_unused:UNUSED_PAD src0_sel:DWORD src1_sel:WORD_1
	v_or_b32_sdwa v4, v7, v6 dst_sel:DWORD dst_unused:UNUSED_PAD src0_sel:DWORD src1_sel:WORD_1
	global_store_dwordx4 v[24:25], v[2:5], off offset:16 sc1
	s_barrier
	s_cbranch_scc0 .LBB0_483

.LBB0_485:
	s_or_b64 exec, exec, s[34:35]
	s_waitcnt vmcnt(3)
	ds_write2_b32 v0, v2, v3 offset1:1
	ds_write2_b32 v0, v4, v5 offset0:2 offset1:3
	s_waitcnt vmcnt(2)
	ds_write2_b32 v21, v6, v7 offset1:1
	ds_write2_b32 v21, v8, v9 offset0:2 offset1:3
	s_waitcnt vmcnt(1)
	ds_write2_b32 v22, v10, v11 offset1:1
	ds_write2_b32 v22, v12, v13 offset0:2 offset1:3
	s_waitcnt vmcnt(0)
	ds_write2_b32 v23, v14, v15 offset1:1
	ds_write2_b32 v23, v16, v17 offset0:2 offset1:3
	s_waitcnt lgkmcnt(0)
	s_barrier
	ds_read2_b32 v[2:3], v20 offset1:65
	ds_read2_b32 v[4:5], v20 offset0:130 offset1:195
	v_add_u32_e32 v8, 0x400, v20
	ds_read2_b32 v[6:7], v8 offset0:4 offset1:69
	ds_read2_b32 v[8:9], v8 offset0:134 offset1:199
	s_lshl_b64 s[12:13], s[26:27], 1
	s_waitcnt lgkmcnt(3)
	v_and_b32_sdwa v26, v2, v193 dst_sel:DWORD dst_unused:UNUSED_PAD src0_sel:WORD_1 src1_sel:DWORD
	s_waitcnt lgkmcnt(2)
	v_and_b32_sdwa v19, v4, v193 dst_sel:DWORD dst_unused:UNUSED_PAD src0_sel:WORD_1 src1_sel:DWORD
	v_add3_u32 v4, v4, v19, s87
	v_and_b32_sdwa v19, v5, v193 dst_sel:DWORD dst_unused:UNUSED_PAD src0_sel:WORD_1 src1_sel:DWORD
	v_add3_u32 v2, v2, v26, s87
	v_and_b32_sdwa v26, v3, v193 dst_sel:DWORD dst_unused:UNUSED_PAD src0_sel:WORD_1 src1_sel:DWORD
	v_add3_u32 v5, v5, v19, s87
	v_or_b32_e32 v24, s22, v147
	v_add3_u32 v3, v3, v26, s87
	v_and_b32_e32 v5, 0xffff0000, v5
	s_add_u32 s12, s9, s12
	v_add_u32_e32 v12, 0x800, v20
	v_ashrrev_i32_e32 v25, 31, v24
	v_and_b32_e32 v19, 0xffff0000, v3
	v_or_b32_sdwa v3, v5, v4 dst_sel:DWORD dst_unused:UNUSED_PAD src0_sel:DWORD src1_sel:WORD_1
	s_waitcnt lgkmcnt(0)
	v_and_b32_sdwa v4, v8, v193 dst_sel:DWORD dst_unused:UNUSED_PAD src0_sel:WORD_1 src1_sel:DWORD
	v_and_b32_sdwa v5, v6, v193 dst_sel:DWORD dst_unused:UNUSED_PAD src0_sel:WORD_1 src1_sel:DWORD
	s_addc_u32 s13, s11, s13
	ds_read2_b32 v[10:11], v12 offset0:8 offset1:73
	ds_read2_b32 v[12:13], v12 offset0:138 offset1:203
	v_lshlrev_b64 v[24:25], 11, v[24:25]
	v_add3_u32 v6, v6, v5, s87
	v_add3_u32 v4, v8, v4, s87
	v_and_b32_sdwa v5, v9, v193 dst_sel:DWORD dst_unused:UNUSED_PAD src0_sel:WORD_1 src1_sel:DWORD
	v_and_b32_sdwa v8, v7, v193 dst_sel:DWORD dst_unused:UNUSED_PAD src0_sel:WORD_1 src1_sel:DWORD
	v_lshl_add_u64 v[24:25], s[12:13], 0, v[24:25]
	s_ashr_i32 s1, s0, 31
	v_add3_u32 v5, v9, v5, s87
	v_add3_u32 v7, v7, v8, s87
	v_lshl_add_u64 v[24:25], s[0:1], 1, v[24:25]
	v_mov_b32_e32 v161, v1
	v_and_b32_e32 v5, 0xffff0000, v5
	v_and_b32_e32 v7, 0xffff0000, v7
	v_add_u32_e32 v16, 0xc00, v20
	v_lshl_add_u64 v[24:25], v[24:25], 0, v[160:161]
	v_or_b32_sdwa v2, v19, v2 dst_sel:DWORD dst_unused:UNUSED_PAD src0_sel:DWORD src1_sel:WORD_1
	v_or_b32_sdwa v5, v5, v4 dst_sel:DWORD dst_unused:UNUSED_PAD src0_sel:DWORD src1_sel:WORD_1
	v_or_b32_sdwa v4, v7, v6 dst_sel:DWORD dst_unused:UNUSED_PAD src0_sel:DWORD src1_sel:WORD_1
	ds_read2_b32 v[14:15], v16 offset0:12 offset1:77
	ds_read2_b32 v[16:17], v16 offset0:142 offset1:207
	global_store_dwordx4 v[24:25], v[2:5], off sc1
	s_add_i32 s8, s8, s44
	s_cmpk_lt_i32 s8, 0x100
	s_waitcnt lgkmcnt(3)
	v_and_b32_sdwa v3, v10, v193 dst_sel:DWORD dst_unused:UNUSED_PAD src0_sel:WORD_1 src1_sel:DWORD
	v_add3_u32 v4, v10, v3, s87
	s_waitcnt lgkmcnt(2)
	v_and_b32_sdwa v3, v13, v193 dst_sel:DWORD dst_unused:UNUSED_PAD src0_sel:WORD_1 src1_sel:DWORD
	v_and_b32_sdwa v5, v11, v193 dst_sel:DWORD dst_unused:UNUSED_PAD src0_sel:WORD_1 src1_sel:DWORD
	v_and_b32_sdwa v2, v12, v193 dst_sel:DWORD dst_unused:UNUSED_PAD src0_sel:WORD_1 src1_sel:DWORD
	v_add3_u32 v3, v13, v3, s87
	v_add3_u32 v5, v11, v5, s87
	v_add3_u32 v2, v12, v2, s87
	v_and_b32_e32 v3, 0xffff0000, v3
	v_and_b32_e32 v5, 0xffff0000, v5
	v_or_b32_sdwa v3, v3, v2 dst_sel:DWORD dst_unused:UNUSED_PAD src0_sel:DWORD src1_sel:WORD_1
	v_or_b32_sdwa v2, v5, v4 dst_sel:DWORD dst_unused:UNUSED_PAD src0_sel:DWORD src1_sel:WORD_1
	s_waitcnt lgkmcnt(1)
	v_and_b32_sdwa v5, v14, v193 dst_sel:DWORD dst_unused:UNUSED_PAD src0_sel:WORD_1 src1_sel:DWORD
	v_add3_u32 v6, v14, v5, s87
	s_waitcnt lgkmcnt(0)
	v_and_b32_sdwa v5, v17, v193 dst_sel:DWORD dst_unused:UNUSED_PAD src0_sel:WORD_1 src1_sel:DWORD
	v_and_b32_sdwa v7, v15, v193 dst_sel:DWORD dst_unused:UNUSED_PAD src0_sel:WORD_1 src1_sel:DWORD
	v_and_b32_sdwa v4, v16, v193 dst_sel:DWORD dst_unused:UNUSED_PAD src0_sel:WORD_1 src1_sel:DWORD
	v_add3_u32 v5, v17, v5, s87
	v_add3_u32 v7, v15, v7, s87
	v_add3_u32 v4, v16, v4, s87
	v_and_b32_e32 v5, 0xffff0000, v5
	v_and_b32_e32 v7, 0xffff0000, v7
	v_or_b32_sdwa v5, v5, v4 dst_sel:DWORD dst_unused:UNUSED_PAD src0_sel:DWORD src1_sel:WORD_1
	v_or_b32_sdwa v4, v7, v6 dst_sel:DWORD dst_unused:UNUSED_PAD src0_sel:DWORD src1_sel:WORD_1
	global_store_dwordx4 v[24:25], v[2:5], off offset:16 sc1
	s_barrier
	s_cbranch_scc0 .LBB0_488

.LBB0_490:
	s_or_b64 exec, exec, s[34:35]
	s_waitcnt vmcnt(3)
	ds_write2_b32 v0, v2, v3 offset1:1
	ds_write2_b32 v0, v4, v5 offset0:2 offset1:3
	s_waitcnt vmcnt(2)
	ds_write2_b32 v21, v6, v7 offset1:1
	ds_write2_b32 v21, v8, v9 offset0:2 offset1:3
	s_waitcnt vmcnt(1)
	ds_write2_b32 v22, v10, v11 offset1:1
	ds_write2_b32 v22, v12, v13 offset0:2 offset1:3
	s_waitcnt vmcnt(0)
	ds_write2_b32 v23, v14, v15 offset1:1
	ds_write2_b32 v23, v16, v17 offset0:2 offset1:3
	s_waitcnt lgkmcnt(0)
	s_barrier
	ds_read2_b32 v[2:3], v20 offset1:65
	ds_read2_b32 v[4:5], v20 offset0:130 offset1:195
	v_add_u32_e32 v8, 0x400, v20
	ds_read2_b32 v[6:7], v8 offset0:4 offset1:69
	ds_read2_b32 v[8:9], v8 offset0:134 offset1:199
	s_lshl_b64 s[12:13], s[26:27], 1
	s_waitcnt lgkmcnt(3)
	v_and_b32_sdwa v26, v2, v193 dst_sel:DWORD dst_unused:UNUSED_PAD src0_sel:WORD_1 src1_sel:DWORD
	s_waitcnt lgkmcnt(2)
	v_and_b32_sdwa v19, v4, v193 dst_sel:DWORD dst_unused:UNUSED_PAD src0_sel:WORD_1 src1_sel:DWORD
	v_add3_u32 v4, v4, v19, s87
	v_and_b32_sdwa v19, v5, v193 dst_sel:DWORD dst_unused:UNUSED_PAD src0_sel:WORD_1 src1_sel:DWORD
	v_add3_u32 v2, v2, v26, s87
	v_and_b32_sdwa v26, v3, v193 dst_sel:DWORD dst_unused:UNUSED_PAD src0_sel:WORD_1 src1_sel:DWORD
	v_add3_u32 v5, v5, v19, s87
	v_or_b32_e32 v24, s22, v147
	v_add3_u32 v3, v3, v26, s87
	v_and_b32_e32 v5, 0xffff0000, v5
	s_add_u32 s12, s9, s12
	v_add_u32_e32 v12, 0x800, v20
	v_ashrrev_i32_e32 v25, 31, v24
	v_and_b32_e32 v19, 0xffff0000, v3
	v_or_b32_sdwa v3, v5, v4 dst_sel:DWORD dst_unused:UNUSED_PAD src0_sel:DWORD src1_sel:WORD_1
	s_waitcnt lgkmcnt(0)
	v_and_b32_sdwa v4, v8, v193 dst_sel:DWORD dst_unused:UNUSED_PAD src0_sel:WORD_1 src1_sel:DWORD
	v_and_b32_sdwa v5, v6, v193 dst_sel:DWORD dst_unused:UNUSED_PAD src0_sel:WORD_1 src1_sel:DWORD
	s_addc_u32 s13, s11, s13
	ds_read2_b32 v[10:11], v12 offset0:8 offset1:73
	ds_read2_b32 v[12:13], v12 offset0:138 offset1:203
	v_lshlrev_b64 v[24:25], 11, v[24:25]
	v_add3_u32 v6, v6, v5, s87
	v_add3_u32 v4, v8, v4, s87
	v_and_b32_sdwa v5, v9, v193 dst_sel:DWORD dst_unused:UNUSED_PAD src0_sel:WORD_1 src1_sel:DWORD
	v_and_b32_sdwa v8, v7, v193 dst_sel:DWORD dst_unused:UNUSED_PAD src0_sel:WORD_1 src1_sel:DWORD
	v_lshl_add_u64 v[24:25], s[12:13], 0, v[24:25]
	s_ashr_i32 s1, s0, 31
	v_add3_u32 v5, v9, v5, s87
	v_add3_u32 v7, v7, v8, s87
	v_lshl_add_u64 v[24:25], s[0:1], 1, v[24:25]
	v_mov_b32_e32 v161, v1
	v_and_b32_e32 v5, 0xffff0000, v5
	v_and_b32_e32 v7, 0xffff0000, v7
	v_add_u32_e32 v16, 0xc00, v20
	v_lshl_add_u64 v[24:25], v[24:25], 0, v[160:161]
	v_or_b32_sdwa v2, v19, v2 dst_sel:DWORD dst_unused:UNUSED_PAD src0_sel:DWORD src1_sel:WORD_1
	v_or_b32_sdwa v5, v5, v4 dst_sel:DWORD dst_unused:UNUSED_PAD src0_sel:DWORD src1_sel:WORD_1
	v_or_b32_sdwa v4, v7, v6 dst_sel:DWORD dst_unused:UNUSED_PAD src0_sel:DWORD src1_sel:WORD_1
	ds_read2_b32 v[14:15], v16 offset0:12 offset1:77
	ds_read2_b32 v[16:17], v16 offset0:142 offset1:207
	global_store_dwordx4 v[24:25], v[2:5], off sc1
	s_add_i32 s8, s8, s44
	s_cmpk_lt_i32 s8, 0x400
	s_waitcnt lgkmcnt(3)
	v_and_b32_sdwa v3, v10, v193 dst_sel:DWORD dst_unused:UNUSED_PAD src0_sel:WORD_1 src1_sel:DWORD
	v_add3_u32 v4, v10, v3, s87
	s_waitcnt lgkmcnt(2)
	v_and_b32_sdwa v3, v13, v193 dst_sel:DWORD dst_unused:UNUSED_PAD src0_sel:WORD_1 src1_sel:DWORD
	v_and_b32_sdwa v5, v11, v193 dst_sel:DWORD dst_unused:UNUSED_PAD src0_sel:WORD_1 src1_sel:DWORD
	v_and_b32_sdwa v2, v12, v193 dst_sel:DWORD dst_unused:UNUSED_PAD src0_sel:WORD_1 src1_sel:DWORD
	v_add3_u32 v3, v13, v3, s87
	v_add3_u32 v5, v11, v5, s87
	v_add3_u32 v2, v12, v2, s87
	v_and_b32_e32 v3, 0xffff0000, v3
	v_and_b32_e32 v5, 0xffff0000, v5
	v_or_b32_sdwa v3, v3, v2 dst_sel:DWORD dst_unused:UNUSED_PAD src0_sel:DWORD src1_sel:WORD_1
	v_or_b32_sdwa v2, v5, v4 dst_sel:DWORD dst_unused:UNUSED_PAD src0_sel:DWORD src1_sel:WORD_1
	s_waitcnt lgkmcnt(1)
	v_and_b32_sdwa v5, v14, v193 dst_sel:DWORD dst_unused:UNUSED_PAD src0_sel:WORD_1 src1_sel:DWORD
	v_add3_u32 v6, v14, v5, s87
	s_waitcnt lgkmcnt(0)
	v_and_b32_sdwa v5, v17, v193 dst_sel:DWORD dst_unused:UNUSED_PAD src0_sel:WORD_1 src1_sel:DWORD
	v_and_b32_sdwa v7, v15, v193 dst_sel:DWORD dst_unused:UNUSED_PAD src0_sel:WORD_1 src1_sel:DWORD
	v_and_b32_sdwa v4, v16, v193 dst_sel:DWORD dst_unused:UNUSED_PAD src0_sel:WORD_1 src1_sel:DWORD
	v_add3_u32 v5, v17, v5, s87
	v_add3_u32 v7, v15, v7, s87
	v_add3_u32 v4, v16, v4, s87
	v_and_b32_e32 v5, 0xffff0000, v5
	v_and_b32_e32 v7, 0xffff0000, v7
	v_or_b32_sdwa v5, v5, v4 dst_sel:DWORD dst_unused:UNUSED_PAD src0_sel:DWORD src1_sel:WORD_1
	v_or_b32_sdwa v4, v7, v6 dst_sel:DWORD dst_unused:UNUSED_PAD src0_sel:DWORD src1_sel:WORD_1
	global_store_dwordx4 v[24:25], v[2:5], off offset:16 sc1
	s_barrier
	s_cbranch_scc0 .LBB0_493

.LBB0_495:
	s_or_b64 exec, exec, s[34:35]
	s_waitcnt vmcnt(3)
	ds_write2_b32 v0, v2, v3 offset1:1
	ds_write2_b32 v0, v4, v5 offset0:2 offset1:3
	s_waitcnt vmcnt(2)
	ds_write2_b32 v21, v6, v7 offset1:1
	ds_write2_b32 v21, v8, v9 offset0:2 offset1:3
	s_waitcnt vmcnt(1)
	ds_write2_b32 v22, v10, v11 offset1:1
	ds_write2_b32 v22, v12, v13 offset0:2 offset1:3
	s_waitcnt vmcnt(0)
	ds_write2_b32 v23, v14, v15 offset1:1
	ds_write2_b32 v23, v16, v17 offset0:2 offset1:3
	s_waitcnt lgkmcnt(0)
	s_barrier
	ds_read2_b32 v[2:3], v20 offset1:65
	ds_read2_b32 v[4:5], v20 offset0:130 offset1:195
	v_add_u32_e32 v8, 0x400, v20
	ds_read2_b32 v[6:7], v8 offset0:4 offset1:69
	ds_read2_b32 v[8:9], v8 offset0:134 offset1:199
	s_lshl_b64 s[12:13], s[26:27], 1
	s_waitcnt lgkmcnt(3)
	v_and_b32_sdwa v26, v2, v193 dst_sel:DWORD dst_unused:UNUSED_PAD src0_sel:WORD_1 src1_sel:DWORD
	s_waitcnt lgkmcnt(2)
	v_and_b32_sdwa v19, v4, v193 dst_sel:DWORD dst_unused:UNUSED_PAD src0_sel:WORD_1 src1_sel:DWORD
	v_add3_u32 v4, v4, v19, s87
	v_and_b32_sdwa v19, v5, v193 dst_sel:DWORD dst_unused:UNUSED_PAD src0_sel:WORD_1 src1_sel:DWORD
	v_add3_u32 v2, v2, v26, s87
	v_and_b32_sdwa v26, v3, v193 dst_sel:DWORD dst_unused:UNUSED_PAD src0_sel:WORD_1 src1_sel:DWORD
	v_add3_u32 v5, v5, v19, s87
	v_or_b32_e32 v24, s22, v147
	v_add3_u32 v3, v3, v26, s87
	v_and_b32_e32 v5, 0xffff0000, v5
	s_add_u32 s12, s9, s12
	v_add_u32_e32 v12, 0x800, v20
	v_ashrrev_i32_e32 v25, 31, v24
	v_and_b32_e32 v19, 0xffff0000, v3
	v_or_b32_sdwa v3, v5, v4 dst_sel:DWORD dst_unused:UNUSED_PAD src0_sel:DWORD src1_sel:WORD_1
	s_waitcnt lgkmcnt(0)
	v_and_b32_sdwa v4, v8, v193 dst_sel:DWORD dst_unused:UNUSED_PAD src0_sel:WORD_1 src1_sel:DWORD
	v_and_b32_sdwa v5, v6, v193 dst_sel:DWORD dst_unused:UNUSED_PAD src0_sel:WORD_1 src1_sel:DWORD
	s_addc_u32 s13, s11, s13
	ds_read2_b32 v[10:11], v12 offset0:8 offset1:73
	ds_read2_b32 v[12:13], v12 offset0:138 offset1:203
	v_lshlrev_b64 v[24:25], 13, v[24:25]
	v_add3_u32 v6, v6, v5, s87
	v_add3_u32 v4, v8, v4, s87
	v_and_b32_sdwa v5, v9, v193 dst_sel:DWORD dst_unused:UNUSED_PAD src0_sel:WORD_1 src1_sel:DWORD
	v_and_b32_sdwa v8, v7, v193 dst_sel:DWORD dst_unused:UNUSED_PAD src0_sel:WORD_1 src1_sel:DWORD
	v_lshl_add_u64 v[24:25], s[12:13], 0, v[24:25]
	s_ashr_i32 s1, s0, 31
	v_add3_u32 v5, v9, v5, s87
	v_add3_u32 v7, v7, v8, s87
	v_lshl_add_u64 v[24:25], s[0:1], 1, v[24:25]
	v_mov_b32_e32 v161, v1
	v_and_b32_e32 v5, 0xffff0000, v5
	v_and_b32_e32 v7, 0xffff0000, v7
	v_add_u32_e32 v16, 0xc00, v20
	v_lshl_add_u64 v[24:25], v[24:25], 0, v[160:161]
	v_or_b32_sdwa v2, v19, v2 dst_sel:DWORD dst_unused:UNUSED_PAD src0_sel:DWORD src1_sel:WORD_1
	v_or_b32_sdwa v5, v5, v4 dst_sel:DWORD dst_unused:UNUSED_PAD src0_sel:DWORD src1_sel:WORD_1
	v_or_b32_sdwa v4, v7, v6 dst_sel:DWORD dst_unused:UNUSED_PAD src0_sel:DWORD src1_sel:WORD_1
	ds_read2_b32 v[14:15], v16 offset0:12 offset1:77
	ds_read2_b32 v[16:17], v16 offset0:142 offset1:207
	global_store_dwordx4 v[24:25], v[2:5], off sc1
	s_add_i32 s8, s8, s44
	s_cmpk_lt_i32 s8, 0x400
	s_waitcnt lgkmcnt(3)
	v_and_b32_sdwa v3, v10, v193 dst_sel:DWORD dst_unused:UNUSED_PAD src0_sel:WORD_1 src1_sel:DWORD
	v_add3_u32 v4, v10, v3, s87
	s_waitcnt lgkmcnt(2)
	v_and_b32_sdwa v3, v13, v193 dst_sel:DWORD dst_unused:UNUSED_PAD src0_sel:WORD_1 src1_sel:DWORD
	v_and_b32_sdwa v5, v11, v193 dst_sel:DWORD dst_unused:UNUSED_PAD src0_sel:WORD_1 src1_sel:DWORD
	v_and_b32_sdwa v2, v12, v193 dst_sel:DWORD dst_unused:UNUSED_PAD src0_sel:WORD_1 src1_sel:DWORD
	v_add3_u32 v3, v13, v3, s87
	v_add3_u32 v5, v11, v5, s87
	v_add3_u32 v2, v12, v2, s87
	v_and_b32_e32 v3, 0xffff0000, v3
	v_and_b32_e32 v5, 0xffff0000, v5
	v_or_b32_sdwa v3, v3, v2 dst_sel:DWORD dst_unused:UNUSED_PAD src0_sel:DWORD src1_sel:WORD_1
	v_or_b32_sdwa v2, v5, v4 dst_sel:DWORD dst_unused:UNUSED_PAD src0_sel:DWORD src1_sel:WORD_1
	s_waitcnt lgkmcnt(1)
	v_and_b32_sdwa v5, v14, v193 dst_sel:DWORD dst_unused:UNUSED_PAD src0_sel:WORD_1 src1_sel:DWORD
	v_add3_u32 v6, v14, v5, s87
	s_waitcnt lgkmcnt(0)
	v_and_b32_sdwa v5, v17, v193 dst_sel:DWORD dst_unused:UNUSED_PAD src0_sel:WORD_1 src1_sel:DWORD
	v_and_b32_sdwa v7, v15, v193 dst_sel:DWORD dst_unused:UNUSED_PAD src0_sel:WORD_1 src1_sel:DWORD
	v_and_b32_sdwa v4, v16, v193 dst_sel:DWORD dst_unused:UNUSED_PAD src0_sel:WORD_1 src1_sel:DWORD
	v_add3_u32 v5, v17, v5, s87
	v_add3_u32 v7, v15, v7, s87
	v_add3_u32 v4, v16, v4, s87
	v_and_b32_e32 v5, 0xffff0000, v5
	v_and_b32_e32 v7, 0xffff0000, v7
	v_or_b32_sdwa v5, v5, v4 dst_sel:DWORD dst_unused:UNUSED_PAD src0_sel:DWORD src1_sel:WORD_1
	v_or_b32_sdwa v4, v7, v6 dst_sel:DWORD dst_unused:UNUSED_PAD src0_sel:DWORD src1_sel:WORD_1
	global_store_dwordx4 v[24:25], v[2:5], off offset:16 sc1
	s_barrier
	s_cbranch_scc0 .LBB0_498

.LBB0_500:
	s_or_b64 exec, exec, s[26:27]
	v_add_u32_e32 v0, 0x400, v20
	s_waitcnt vmcnt(3)
	ds_write2_b32 v21, v2, v3 offset1:1
	ds_write2_b32 v21, v4, v5 offset0:2 offset1:3
	s_waitcnt vmcnt(2)
	ds_write2_b32 v22, v6, v7 offset1:1
	ds_write2_b32 v22, v8, v9 offset0:2 offset1:3
	s_waitcnt vmcnt(1)
	ds_write2_b32 v23, v10, v11 offset1:1
	ds_write2_b32 v23, v12, v13 offset0:2 offset1:3
	s_waitcnt vmcnt(0)
	ds_write2_b32 v24, v14, v15 offset1:1
	ds_write2_b32 v24, v16, v17 offset0:2 offset1:3
	s_waitcnt lgkmcnt(0)
	s_barrier
	ds_read2_b32 v[2:3], v20 offset1:65
	ds_read2_b32 v[4:5], v20 offset0:130 offset1:195
	ds_read2_b32 v[6:7], v0 offset0:4 offset1:69
	ds_read2_b32 v[8:9], v0 offset0:134 offset1:199
	v_add_u32_e32 v0, 0x800, v20
	ds_read2_b32 v[10:11], v0 offset0:8 offset1:73
	ds_read2_b32 v[12:13], v0 offset0:138 offset1:203
	v_add_u32_e32 v0, 0xc00, v20
	ds_read2_b32 v[14:15], v0 offset0:12 offset1:77
	ds_read2_b32 v[16:17], v0 offset0:142 offset1:207
	v_or_b32_e32 v0, s12, v138
	s_lshl_b64 s[22:23], s[22:23], 1
	v_ashrrev_i32_e32 v26, 5, v0
	s_add_u32 s22, s9, s22
	v_ashrrev_i32_e32 v27, 31, v26
	v_or_b32_e32 v28, s0, v147
	s_addc_u32 s23, s11, s23
	v_ashrrev_i32_e32 v29, 31, v28
	v_lshlrev_b64 v[26:27], 13, v[26:27]
	v_lshlrev_b64 v[28:29], 6, v[28:29]
	v_lshl_add_u64 v[26:27], s[22:23], 0, v[26:27]
	v_lshl_add_u64 v[26:27], v[26:27], 0, v[28:29]
	v_lshlrev_b32_e32 v0, 1, v140
	v_lshl_add_u64 v[26:27], v[26:27], 0, v[0:1]
	s_waitcnt lgkmcnt(6)
	v_and_b32_sdwa v0, v4, v193 dst_sel:DWORD dst_unused:UNUSED_PAD src0_sel:WORD_1 src1_sel:DWORD
	v_and_b32_sdwa v19, v2, v193 dst_sel:DWORD dst_unused:UNUSED_PAD src0_sel:WORD_1 src1_sel:DWORD
	v_add3_u32 v0, v4, v0, s87
	v_and_b32_sdwa v4, v5, v193 dst_sel:DWORD dst_unused:UNUSED_PAD src0_sel:WORD_1 src1_sel:DWORD
	v_add3_u32 v2, v2, v19, s87
	v_and_b32_sdwa v19, v3, v193 dst_sel:DWORD dst_unused:UNUSED_PAD src0_sel:WORD_1 src1_sel:DWORD
	v_add3_u32 v4, v5, v4, s87
	v_add3_u32 v3, v3, v19, s87
	v_and_b32_e32 v4, 0xffff0000, v4
	v_and_b32_e32 v5, 0xffff0000, v3
	v_or_b32_sdwa v3, v4, v0 dst_sel:DWORD dst_unused:UNUSED_PAD src0_sel:DWORD src1_sel:WORD_1
	s_waitcnt lgkmcnt(5)
	v_and_b32_sdwa v4, v6, v193 dst_sel:DWORD dst_unused:UNUSED_PAD src0_sel:WORD_1 src1_sel:DWORD
	v_or_b32_sdwa v2, v5, v2 dst_sel:DWORD dst_unused:UNUSED_PAD src0_sel:DWORD src1_sel:WORD_1
	v_add3_u32 v4, v6, v4, s87
	s_waitcnt lgkmcnt(4)
	v_and_b32_sdwa v5, v9, v193 dst_sel:DWORD dst_unused:UNUSED_PAD src0_sel:WORD_1 src1_sel:DWORD
	v_and_b32_sdwa v6, v7, v193 dst_sel:DWORD dst_unused:UNUSED_PAD src0_sel:WORD_1 src1_sel:DWORD
	v_and_b32_sdwa v0, v8, v193 dst_sel:DWORD dst_unused:UNUSED_PAD src0_sel:WORD_1 src1_sel:DWORD
	v_add3_u32 v5, v9, v5, s87
	v_add3_u32 v6, v7, v6, s87
	v_add3_u32 v0, v8, v0, s87
	v_and_b32_e32 v5, 0xffff0000, v5
	v_and_b32_e32 v6, 0xffff0000, v6
	v_or_b32_sdwa v5, v5, v0 dst_sel:DWORD dst_unused:UNUSED_PAD src0_sel:DWORD src1_sel:WORD_1
	v_or_b32_sdwa v4, v6, v4 dst_sel:DWORD dst_unused:UNUSED_PAD src0_sel:DWORD src1_sel:WORD_1
	global_store_dwordx4 v[26:27], v[2:5], off sc1
	s_waitcnt lgkmcnt(2)
	v_and_b32_sdwa v0, v12, v193 dst_sel:DWORD dst_unused:UNUSED_PAD src0_sel:WORD_1 src1_sel:DWORD
	v_add3_u32 v0, v12, v0, s87
	v_and_b32_sdwa v3, v13, v193 dst_sel:DWORD dst_unused:UNUSED_PAD src0_sel:WORD_1 src1_sel:DWORD
	v_and_b32_sdwa v4, v11, v193 dst_sel:DWORD dst_unused:UNUSED_PAD src0_sel:WORD_1 src1_sel:DWORD
	v_and_b32_sdwa v2, v10, v193 dst_sel:DWORD dst_unused:UNUSED_PAD src0_sel:WORD_1 src1_sel:DWORD
	v_add3_u32 v3, v13, v3, s87
	v_add3_u32 v4, v11, v4, s87
	v_add3_u32 v2, v10, v2, s87
	v_and_b32_e32 v3, 0xffff0000, v3
	v_and_b32_e32 v4, 0xffff0000, v4
	s_waitcnt lgkmcnt(0)
	v_and_b32_sdwa v5, v17, v193 dst_sel:DWORD dst_unused:UNUSED_PAD src0_sel:WORD_1 src1_sel:DWORD
	v_and_b32_sdwa v6, v15, v193 dst_sel:DWORD dst_unused:UNUSED_PAD src0_sel:WORD_1 src1_sel:DWORD
	v_or_b32_sdwa v3, v3, v0 dst_sel:DWORD dst_unused:UNUSED_PAD src0_sel:DWORD src1_sel:WORD_1
	v_or_b32_sdwa v2, v4, v2 dst_sel:DWORD dst_unused:UNUSED_PAD src0_sel:DWORD src1_sel:WORD_1
	v_and_b32_sdwa v0, v16, v193 dst_sel:DWORD dst_unused:UNUSED_PAD src0_sel:WORD_1 src1_sel:DWORD
	v_and_b32_sdwa v4, v14, v193 dst_sel:DWORD dst_unused:UNUSED_PAD src0_sel:WORD_1 src1_sel:DWORD
	v_add3_u32 v5, v17, v5, s87
	v_add3_u32 v6, v15, v6, s87
	v_add3_u32 v4, v14, v4, s87
	v_add3_u32 v0, v16, v0, s87
	v_and_b32_e32 v5, 0xffff0000, v5
	v_and_b32_e32 v6, 0xffff0000, v6
	s_add_i32 s8, s8, s44
	v_or_b32_sdwa v5, v5, v0 dst_sel:DWORD dst_unused:UNUSED_PAD src0_sel:DWORD src1_sel:WORD_1
	v_or_b32_sdwa v4, v6, v4 dst_sel:DWORD dst_unused:UNUSED_PAD src0_sel:DWORD src1_sel:WORD_1
	s_cmpk_lt_i32 s8, 0x200
	global_store_dwordx4 v[26:27], v[2:5], off offset:16 sc1
	s_barrier
	s_cbranch_scc0 .LBB0_503

.LBB0_505:
	s_ashr_i32 s0, s8, 31
	s_lshr_b32 s0, s0, 29
	s_add_i32 s0, s8, s0
	s_ashr_i32 s0, s0, 3
	s_lshl_b32 s13, s0, 9
	s_sub_i32 s13, s12, s13
	s_ashr_i32 s1, s0, 31
	v_add_u32_e32 v12, s13, v141
	s_lshl_b64 s[22:23], s[0:1], 17
	v_ashrrev_i32_e32 v13, 31, v12
	v_lshl_add_u64 v[10:11], v[142:143], 0, s[22:23]
	v_lshlrev_b64 v[6:7], 8, v[12:13]
	v_lshl_add_u64 v[6:7], v[10:11], 0, v[6:7]
	global_load_dwordx4 v[6:9], v[6:7], off
	v_add_u32_e32 v0, 0x400, v20
	s_lshl_b64 s[0:1], s[0:1], 16
	s_add_u32 s0, s9, s0
	s_addc_u32 s1, s11, s1
	s_add_i32 s8, s8, s44
	s_add_i32 s12, s12, s6
	s_cmpk_lt_i32 s8, 0x100
	s_waitcnt vmcnt(0)
	ds_write2_b32 v2, v6, v7 offset1:1
	ds_write2_b32 v2, v8, v9 offset0:2 offset1:3
	v_add_u32_e32 v6, 16, v12
	v_ashrrev_i32_e32 v7, 31, v6
	v_lshlrev_b64 v[6:7], 8, v[6:7]
	v_lshl_add_u64 v[6:7], v[10:11], 0, v[6:7]
	global_load_dwordx4 v[6:9], v[6:7], off
	s_waitcnt vmcnt(0)
	ds_write2_b32 v3, v6, v7 offset1:1
	ds_write2_b32 v3, v8, v9 offset0:2 offset1:3
	v_add_u32_e32 v6, 32, v12
	v_ashrrev_i32_e32 v7, 31, v6
	v_lshlrev_b64 v[6:7], 8, v[6:7]
	v_lshl_add_u64 v[6:7], v[10:11], 0, v[6:7]
	global_load_dwordx4 v[6:9], v[6:7], off
	s_waitcnt vmcnt(0)
	ds_write2_b32 v4, v6, v7 offset1:1
	ds_write2_b32 v4, v8, v9 offset0:2 offset1:3
	v_add_u32_e32 v6, 48, v12
	v_ashrrev_i32_e32 v7, 31, v6
	v_lshlrev_b64 v[6:7], 8, v[6:7]
	v_lshl_add_u64 v[6:7], v[10:11], 0, v[6:7]
	global_load_dwordx4 v[6:9], v[6:7], off
	s_waitcnt vmcnt(0)
	ds_write2_b32 v5, v6, v7 offset1:1
	ds_write2_b32 v5, v8, v9 offset0:2 offset1:3
	s_waitcnt lgkmcnt(0)
	s_barrier
	ds_read2_b32 v[6:7], v20 offset1:65
	ds_read2_b32 v[8:9], v20 offset0:130 offset1:195
	ds_read2_b32 v[10:11], v0 offset0:4 offset1:69
	ds_read2_b32 v[12:13], v0 offset0:134 offset1:199
	v_add_u32_e32 v0, 0x800, v20
	ds_read2_b32 v[14:15], v0 offset0:8 offset1:73
	ds_read2_b32 v[16:17], v0 offset0:138 offset1:203
	v_add_u32_e32 v0, 0xc00, v20
	ds_read2_b32 v[22:23], v0 offset0:12 offset1:77
	ds_read2_b32 v[24:25], v0 offset0:142 offset1:207
	v_add_u32_e32 v0, s13, v138
	v_ashrrev_i32_e32 v26, 5, v0
	v_ashrrev_i32_e32 v27, 31, v26
	v_lshlrev_b64 v[26:27], 12, v[26:27]
	v_lshl_add_u64 v[26:27], s[0:1], 0, v[26:27]
	v_lshl_add_u64 v[26:27], v[26:27], 0, v[144:145]
	v_lshlrev_b32_e32 v0, 1, v140
	v_lshl_add_u64 v[26:27], v[26:27], 0, v[0:1]
	s_waitcnt lgkmcnt(6)
	v_and_b32_sdwa v0, v8, v193 dst_sel:DWORD dst_unused:UNUSED_PAD src0_sel:WORD_1 src1_sel:DWORD
	v_and_b32_sdwa v19, v6, v193 dst_sel:DWORD dst_unused:UNUSED_PAD src0_sel:WORD_1 src1_sel:DWORD
	v_add3_u32 v0, v8, v0, s87
	v_and_b32_sdwa v8, v9, v193 dst_sel:DWORD dst_unused:UNUSED_PAD src0_sel:WORD_1 src1_sel:DWORD
	v_add3_u32 v6, v6, v19, s87
	v_and_b32_sdwa v19, v7, v193 dst_sel:DWORD dst_unused:UNUSED_PAD src0_sel:WORD_1 src1_sel:DWORD
	v_add3_u32 v8, v9, v8, s87
	v_add3_u32 v7, v7, v19, s87
	v_and_b32_e32 v8, 0xffff0000, v8
	v_and_b32_e32 v9, 0xffff0000, v7
	v_or_b32_sdwa v7, v8, v0 dst_sel:DWORD dst_unused:UNUSED_PAD src0_sel:DWORD src1_sel:WORD_1
	s_waitcnt lgkmcnt(5)
	v_and_b32_sdwa v8, v10, v193 dst_sel:DWORD dst_unused:UNUSED_PAD src0_sel:WORD_1 src1_sel:DWORD
	v_or_b32_sdwa v6, v9, v6 dst_sel:DWORD dst_unused:UNUSED_PAD src0_sel:DWORD src1_sel:WORD_1
	v_add3_u32 v8, v10, v8, s87
	s_waitcnt lgkmcnt(4)
	v_and_b32_sdwa v9, v13, v193 dst_sel:DWORD dst_unused:UNUSED_PAD src0_sel:WORD_1 src1_sel:DWORD
	v_and_b32_sdwa v10, v11, v193 dst_sel:DWORD dst_unused:UNUSED_PAD src0_sel:WORD_1 src1_sel:DWORD
	v_and_b32_sdwa v0, v12, v193 dst_sel:DWORD dst_unused:UNUSED_PAD src0_sel:WORD_1 src1_sel:DWORD
	v_add3_u32 v9, v13, v9, s87
	v_add3_u32 v10, v11, v10, s87
	v_add3_u32 v0, v12, v0, s87
	v_and_b32_e32 v9, 0xffff0000, v9
	v_and_b32_e32 v10, 0xffff0000, v10
	v_or_b32_sdwa v9, v9, v0 dst_sel:DWORD dst_unused:UNUSED_PAD src0_sel:DWORD src1_sel:WORD_1
	v_or_b32_sdwa v8, v10, v8 dst_sel:DWORD dst_unused:UNUSED_PAD src0_sel:DWORD src1_sel:WORD_1
	global_store_dwordx4 v[26:27], v[6:9], off sc1
	s_waitcnt lgkmcnt(2)
	v_and_b32_sdwa v0, v16, v193 dst_sel:DWORD dst_unused:UNUSED_PAD src0_sel:WORD_1 src1_sel:DWORD
	v_add3_u32 v0, v16, v0, s87
	v_and_b32_sdwa v7, v17, v193 dst_sel:DWORD dst_unused:UNUSED_PAD src0_sel:WORD_1 src1_sel:DWORD
	v_and_b32_sdwa v8, v15, v193 dst_sel:DWORD dst_unused:UNUSED_PAD src0_sel:WORD_1 src1_sel:DWORD
	v_and_b32_sdwa v6, v14, v193 dst_sel:DWORD dst_unused:UNUSED_PAD src0_sel:WORD_1 src1_sel:DWORD
	v_add3_u32 v7, v17, v7, s87
	v_add3_u32 v8, v15, v8, s87
	v_add3_u32 v6, v14, v6, s87
	v_and_b32_e32 v7, 0xffff0000, v7
	v_and_b32_e32 v8, 0xffff0000, v8
	s_waitcnt lgkmcnt(0)
	v_and_b32_sdwa v9, v25, v193 dst_sel:DWORD dst_unused:UNUSED_PAD src0_sel:WORD_1 src1_sel:DWORD
	v_and_b32_sdwa v10, v23, v193 dst_sel:DWORD dst_unused:UNUSED_PAD src0_sel:WORD_1 src1_sel:DWORD
	v_or_b32_sdwa v7, v7, v0 dst_sel:DWORD dst_unused:UNUSED_PAD src0_sel:DWORD src1_sel:WORD_1
	v_or_b32_sdwa v6, v8, v6 dst_sel:DWORD dst_unused:UNUSED_PAD src0_sel:DWORD src1_sel:WORD_1
	v_and_b32_sdwa v0, v24, v193 dst_sel:DWORD dst_unused:UNUSED_PAD src0_sel:WORD_1 src1_sel:DWORD
	v_and_b32_sdwa v8, v22, v193 dst_sel:DWORD dst_unused:UNUSED_PAD src0_sel:WORD_1 src1_sel:DWORD
	v_add3_u32 v9, v25, v9, s87
	v_add3_u32 v10, v23, v10, s87
	v_add3_u32 v8, v22, v8, s87
	v_add3_u32 v0, v24, v0, s87
	v_and_b32_e32 v9, 0xffff0000, v9
	v_and_b32_e32 v10, 0xffff0000, v10
	v_or_b32_sdwa v9, v9, v0 dst_sel:DWORD dst_unused:UNUSED_PAD src0_sel:DWORD src1_sel:WORD_1
	v_or_b32_sdwa v8, v10, v8 dst_sel:DWORD dst_unused:UNUSED_PAD src0_sel:DWORD src1_sel:WORD_1
	global_store_dwordx4 v[26:27], v[6:9], off offset:16 sc1
	s_barrier
	s_cbranch_scc1 .LBB0_505

.LBB0_508:
	global_load_dwordx4 v[10:13], v[2:3], off
	v_add_u32_e32 v9, 0x400, v20
	s_add_i32 s0, s0, s44
	s_cmp_lt_i32 s0, 64
	s_waitcnt vmcnt(0)
	ds_write2_b32 v0, v10, v11 offset1:1
	ds_write2_b32 v0, v12, v13 offset0:2 offset1:3
	v_add_co_u32_e32 v10, vcc, 0x1000, v2
	s_nop 1
	v_addc_co_u32_e32 v11, vcc, 0, v3, vcc
	global_load_dwordx4 v[10:13], v[10:11], off
	s_waitcnt vmcnt(0)
	ds_write2_b32 v6, v10, v11 offset1:1
	ds_write2_b32 v6, v12, v13 offset0:2 offset1:3
	v_add_co_u32_e32 v10, vcc, 0x2000, v2
	s_nop 1
	v_addc_co_u32_e32 v11, vcc, 0, v3, vcc
	global_load_dwordx4 v[10:13], v[10:11], off
	s_waitcnt vmcnt(0)
	ds_write2_b32 v7, v10, v11 offset1:1
	ds_write2_b32 v7, v12, v13 offset0:2 offset1:3
	v_add_co_u32_e32 v10, vcc, 0x3000, v2
	s_nop 1
	v_addc_co_u32_e32 v11, vcc, 0, v3, vcc
	global_load_dwordx4 v[10:13], v[10:11], off
	v_lshl_add_u64 v[2:3], v[2:3], 0, s[22:23]
	s_waitcnt vmcnt(0)
	ds_write2_b32 v8, v10, v11 offset1:1
	ds_write2_b32 v8, v12, v13 offset0:2 offset1:3
	s_waitcnt lgkmcnt(0)
	s_barrier
	ds_read2_b32 v[10:11], v20 offset1:65
	ds_read2_b32 v[12:13], v20 offset0:130 offset1:195
	ds_read2_b32 v[14:15], v9 offset0:4 offset1:69
	ds_read2_b32 v[16:17], v9 offset0:134 offset1:199
	v_add_u32_e32 v9, 0x800, v20
	ds_read2_b32 v[18:19], v9 offset0:8 offset1:73
	ds_read2_b32 v[22:23], v9 offset0:138 offset1:203
	v_add_u32_e32 v9, 0xc00, v20
	ds_read2_b32 v[24:25], v9 offset0:12 offset1:77
	ds_read2_b32 v[26:27], v9 offset0:142 offset1:207
	s_waitcnt lgkmcnt(6)
	v_and_b32_sdwa v9, v12, v193 dst_sel:DWORD dst_unused:UNUSED_PAD src0_sel:WORD_1 src1_sel:DWORD
	v_and_b32_sdwa v21, v10, v193 dst_sel:DWORD dst_unused:UNUSED_PAD src0_sel:WORD_1 src1_sel:DWORD
	v_add3_u32 v9, v12, v9, s87
	v_and_b32_sdwa v12, v13, v193 dst_sel:DWORD dst_unused:UNUSED_PAD src0_sel:WORD_1 src1_sel:DWORD
	v_add3_u32 v10, v10, v21, s87
	v_and_b32_sdwa v21, v11, v193 dst_sel:DWORD dst_unused:UNUSED_PAD src0_sel:WORD_1 src1_sel:DWORD
	v_add3_u32 v12, v13, v12, s87
	v_add3_u32 v11, v11, v21, s87
	v_and_b32_e32 v12, 0xffff0000, v12
	v_and_b32_e32 v13, 0xffff0000, v11
	v_or_b32_sdwa v11, v12, v9 dst_sel:DWORD dst_unused:UNUSED_PAD src0_sel:DWORD src1_sel:WORD_1
	s_waitcnt lgkmcnt(5)
	v_and_b32_sdwa v12, v14, v193 dst_sel:DWORD dst_unused:UNUSED_PAD src0_sel:WORD_1 src1_sel:DWORD
	v_or_b32_sdwa v10, v13, v10 dst_sel:DWORD dst_unused:UNUSED_PAD src0_sel:DWORD src1_sel:WORD_1
	v_add3_u32 v12, v14, v12, s87
	s_waitcnt lgkmcnt(4)
	v_and_b32_sdwa v13, v17, v193 dst_sel:DWORD dst_unused:UNUSED_PAD src0_sel:WORD_1 src1_sel:DWORD
	v_and_b32_sdwa v14, v15, v193 dst_sel:DWORD dst_unused:UNUSED_PAD src0_sel:WORD_1 src1_sel:DWORD
	v_and_b32_sdwa v9, v16, v193 dst_sel:DWORD dst_unused:UNUSED_PAD src0_sel:WORD_1 src1_sel:DWORD
	v_add3_u32 v13, v17, v13, s87
	v_add3_u32 v14, v15, v14, s87
	v_add3_u32 v9, v16, v9, s87
	v_and_b32_e32 v13, 0xffff0000, v13
	v_and_b32_e32 v14, 0xffff0000, v14
	v_or_b32_sdwa v13, v13, v9 dst_sel:DWORD dst_unused:UNUSED_PAD src0_sel:DWORD src1_sel:WORD_1
	v_or_b32_sdwa v12, v14, v12 dst_sel:DWORD dst_unused:UNUSED_PAD src0_sel:DWORD src1_sel:WORD_1
	global_store_dwordx4 v[4:5], v[10:13], off offset:-16
	s_waitcnt lgkmcnt(2)
	v_and_b32_sdwa v9, v22, v193 dst_sel:DWORD dst_unused:UNUSED_PAD src0_sel:WORD_1 src1_sel:DWORD
	v_add3_u32 v9, v22, v9, s87
	v_and_b32_sdwa v11, v23, v193 dst_sel:DWORD dst_unused:UNUSED_PAD src0_sel:WORD_1 src1_sel:DWORD
	v_and_b32_sdwa v12, v19, v193 dst_sel:DWORD dst_unused:UNUSED_PAD src0_sel:WORD_1 src1_sel:DWORD
	v_and_b32_sdwa v10, v18, v193 dst_sel:DWORD dst_unused:UNUSED_PAD src0_sel:WORD_1 src1_sel:DWORD
	v_add3_u32 v11, v23, v11, s87
	v_add3_u32 v12, v19, v12, s87
	v_add3_u32 v10, v18, v10, s87
	v_and_b32_e32 v11, 0xffff0000, v11
	v_and_b32_e32 v12, 0xffff0000, v12
	s_waitcnt lgkmcnt(0)
	v_and_b32_sdwa v13, v27, v193 dst_sel:DWORD dst_unused:UNUSED_PAD src0_sel:WORD_1 src1_sel:DWORD
	v_and_b32_sdwa v14, v25, v193 dst_sel:DWORD dst_unused:UNUSED_PAD src0_sel:WORD_1 src1_sel:DWORD
	v_or_b32_sdwa v11, v11, v9 dst_sel:DWORD dst_unused:UNUSED_PAD src0_sel:DWORD src1_sel:WORD_1
	v_or_b32_sdwa v10, v12, v10 dst_sel:DWORD dst_unused:UNUSED_PAD src0_sel:DWORD src1_sel:WORD_1
	v_and_b32_sdwa v9, v26, v193 dst_sel:DWORD dst_unused:UNUSED_PAD src0_sel:WORD_1 src1_sel:DWORD
	v_and_b32_sdwa v12, v24, v193 dst_sel:DWORD dst_unused:UNUSED_PAD src0_sel:WORD_1 src1_sel:DWORD
	v_add3_u32 v13, v27, v13, s87
	v_add3_u32 v14, v25, v14, s87
	v_add3_u32 v12, v24, v12, s87
	v_add3_u32 v9, v26, v9, s87
	v_and_b32_e32 v13, 0xffff0000, v13
	v_and_b32_e32 v14, 0xffff0000, v14
	v_or_b32_sdwa v13, v13, v9 dst_sel:DWORD dst_unused:UNUSED_PAD src0_sel:DWORD src1_sel:WORD_1
	v_or_b32_sdwa v12, v14, v12 dst_sel:DWORD dst_unused:UNUSED_PAD src0_sel:DWORD src1_sel:WORD_1
	global_store_dwordx4 v[4:5], v[10:13], off sc1
	v_lshl_add_u64 v[4:5], v[4:5], 0, s[26:27]
	s_barrier
	s_cbranch_scc1 .LBB0_508

.LBB0_511:
	global_load_dwordx4 v[8:11], v[4:5], off
	global_load_dwordx4 v[12:15], v[4:5], off offset:-16
	v_lshl_add_u64 v[2:3], v[2:3], 0, s[0:1]
	s_mov_b64 s[8:9], 0x1fffff
	v_cmp_lt_u64_e32 vcc, s[8:9], v[2:3]
	v_lshl_add_u64 v[4:5], v[4:5], 0, s[22:23]
	s_or_b64 s[26:27], vcc, s[26:27]
	s_waitcnt vmcnt(0)
	v_and_b32_sdwa v0, v14, v193 dst_sel:DWORD dst_unused:UNUSED_PAD src0_sel:WORD_1 src1_sel:DWORD
	v_and_b32_sdwa v16, v12, v193 dst_sel:DWORD dst_unused:UNUSED_PAD src0_sel:WORD_1 src1_sel:DWORD
	v_add3_u32 v0, v14, v0, s87
	v_and_b32_sdwa v14, v15, v193 dst_sel:DWORD dst_unused:UNUSED_PAD src0_sel:WORD_1 src1_sel:DWORD
	v_add3_u32 v12, v12, v16, s87
	v_and_b32_sdwa v16, v13, v193 dst_sel:DWORD dst_unused:UNUSED_PAD src0_sel:WORD_1 src1_sel:DWORD
	v_add3_u32 v14, v15, v14, s87
	v_add3_u32 v13, v13, v16, s87
	v_and_b32_e32 v14, 0xffff0000, v14
	v_and_b32_e32 v15, 0xffff0000, v13
	v_or_b32_sdwa v13, v14, v0 dst_sel:DWORD dst_unused:UNUSED_PAD src0_sel:DWORD src1_sel:WORD_1
	v_and_b32_sdwa v0, v10, v193 dst_sel:DWORD dst_unused:UNUSED_PAD src0_sel:WORD_1 src1_sel:DWORD
	v_and_b32_sdwa v14, v8, v193 dst_sel:DWORD dst_unused:UNUSED_PAD src0_sel:WORD_1 src1_sel:DWORD
	v_add3_u32 v8, v8, v14, s87
	v_add3_u32 v0, v10, v0, s87
	v_and_b32_sdwa v10, v11, v193 dst_sel:DWORD dst_unused:UNUSED_PAD src0_sel:WORD_1 src1_sel:DWORD
	v_and_b32_sdwa v14, v9, v193 dst_sel:DWORD dst_unused:UNUSED_PAD src0_sel:WORD_1 src1_sel:DWORD
	v_add3_u32 v10, v11, v10, s87
	v_add3_u32 v9, v9, v14, s87
	v_and_b32_e32 v10, 0xffff0000, v10
	v_and_b32_e32 v9, 0xffff0000, v9
	v_or_b32_sdwa v12, v15, v12 dst_sel:DWORD dst_unused:UNUSED_PAD src0_sel:DWORD src1_sel:WORD_1
	v_or_b32_sdwa v15, v10, v0 dst_sel:DWORD dst_unused:UNUSED_PAD src0_sel:DWORD src1_sel:WORD_1
	v_or_b32_sdwa v14, v9, v8 dst_sel:DWORD dst_unused:UNUSED_PAD src0_sel:DWORD src1_sel:WORD_1
	global_store_dwordx4 v[6:7], v[12:15], off sc1
	v_lshl_add_u64 v[6:7], v[6:7], 0, s[34:35]
	s_andn2_b64 exec, exec, s[26:27]
	s_cbranch_execnz .LBB0_511
	s_or_b64 exec, exec, s[26:27]

.LBB0_515:
	global_load_dwordx4 v[8:11], v[4:5], off
	global_load_dwordx4 v[12:15], v[4:5], off offset:-16
	v_lshl_add_u64 v[2:3], v[2:3], 0, s[0:1]
	s_mov_b64 s[8:9], 0xfffff
	v_cmp_lt_u64_e32 vcc, s[8:9], v[2:3]
	v_lshl_add_u64 v[4:5], v[4:5], 0, s[22:23]
	s_or_b64 s[26:27], vcc, s[26:27]
	s_waitcnt vmcnt(0)
	v_and_b32_sdwa v0, v14, v193 dst_sel:DWORD dst_unused:UNUSED_PAD src0_sel:WORD_1 src1_sel:DWORD
	v_and_b32_sdwa v16, v12, v193 dst_sel:DWORD dst_unused:UNUSED_PAD src0_sel:WORD_1 src1_sel:DWORD
	v_add3_u32 v0, v14, v0, s87
	v_and_b32_sdwa v14, v15, v193 dst_sel:DWORD dst_unused:UNUSED_PAD src0_sel:WORD_1 src1_sel:DWORD
	v_add3_u32 v12, v12, v16, s87
	v_and_b32_sdwa v16, v13, v193 dst_sel:DWORD dst_unused:UNUSED_PAD src0_sel:WORD_1 src1_sel:DWORD
	v_add3_u32 v14, v15, v14, s87
	v_add3_u32 v13, v13, v16, s87
	v_and_b32_e32 v14, 0xffff0000, v14
	v_and_b32_e32 v15, 0xffff0000, v13
	v_or_b32_sdwa v13, v14, v0 dst_sel:DWORD dst_unused:UNUSED_PAD src0_sel:DWORD src1_sel:WORD_1
	v_and_b32_sdwa v0, v10, v193 dst_sel:DWORD dst_unused:UNUSED_PAD src0_sel:WORD_1 src1_sel:DWORD
	v_and_b32_sdwa v14, v8, v193 dst_sel:DWORD dst_unused:UNUSED_PAD src0_sel:WORD_1 src1_sel:DWORD
	v_add3_u32 v8, v8, v14, s87
	v_add3_u32 v0, v10, v0, s87
	v_and_b32_sdwa v10, v11, v193 dst_sel:DWORD dst_unused:UNUSED_PAD src0_sel:WORD_1 src1_sel:DWORD
	v_and_b32_sdwa v14, v9, v193 dst_sel:DWORD dst_unused:UNUSED_PAD src0_sel:WORD_1 src1_sel:DWORD
	v_add3_u32 v10, v11, v10, s87
	v_add3_u32 v9, v9, v14, s87
	v_and_b32_e32 v10, 0xffff0000, v10
	v_and_b32_e32 v9, 0xffff0000, v9
	v_or_b32_sdwa v12, v15, v12 dst_sel:DWORD dst_unused:UNUSED_PAD src0_sel:DWORD src1_sel:WORD_1
	v_or_b32_sdwa v15, v10, v0 dst_sel:DWORD dst_unused:UNUSED_PAD src0_sel:DWORD src1_sel:WORD_1
	v_or_b32_sdwa v14, v9, v8 dst_sel:DWORD dst_unused:UNUSED_PAD src0_sel:DWORD src1_sel:WORD_1
	global_store_dwordx4 v[6:7], v[12:15], off sc1
	v_lshl_add_u64 v[6:7], v[6:7], 0, s[34:35]
	s_andn2_b64 exec, exec, s[26:27]
	s_cbranch_execnz .LBB0_515
	s_or_b64 exec, exec, s[26:27]
	s_branch .Ltramp_7
